# snake order of MFMAs inside each 8-MFMA group of the GEMM loops so consecutive MFMAs share one operand
# baseline (speedup 1.0000x reference)
.LBB0_180:
	s_add_u32 s62, s60, 0xfffc0080
	s_addc_u32 s63, s61, -1
	s_add_i32 s86, 0, 0x10000
	s_cmp_eq_u32 s85, 12
	s_cselect_b32 vcc_hi, s47, s63
	s_cselect_b32 vcc_lo, s82, s62
	v_add_u32_e32 v142, s86, v145
	s_cselect_b32 s63, s21, s84
	s_cselect_b32 s62, s83, s89
	s_add_i32 s92, 0, 0x14000
	ds_read_b128 v[138:141], v142
	ds_read_b128 v[172:175], v142 offset:1024
	ds_read_b128 v[176:179], v142 offset:2048
	ds_read_b128 v[180:183], v142 offset:3072
	v_add_u32_e32 v142, s92, v145
	ds_read_b128 v[184:187], v142
	ds_read_b128 v[188:191], v142 offset:1024
	ds_read_b128 v[192:195], v142 offset:2048
	ds_read_b128 v[196:199], v142 offset:3072
	v_lshl_add_u64 v[142:143], s[60:61], 0, v[136:137]
	s_add_i32 m0, s68, 0xc000
	ds_read_b128 v[210:213], v148
	ds_read_b128 v[214:217], v148 offset:1024
	ds_read_b128 v[218:221], v148 offset:2048
	ds_read_b128 v[224:227], v148 offset:3072
	ds_read_b128 v[228:231], v148 offset:4096
	ds_read_b128 v[232:235], v148 offset:5120
	ds_read_b128 v[236:239], v148 offset:6144
	ds_read_b128 v[240:243], v148 offset:7168
	global_load_lds_dwordx4 v[142:143], off
	v_lshl_add_u64 v[142:143], s[60:61], 0, v[134:135]
	s_add_i32 m0, s68, 0xe000
	s_nop 0
	global_load_lds_dwordx4 v[142:143], off
	s_waitcnt vmcnt(8)
	s_waitcnt lgkmcnt(0)
	s_barrier
	s_setprio 1
	s_waitcnt lgkmcnt(0)
	v_mfma_f32_16x16x32_bf16 v[124:127], v[138:141], v[210:213], v[124:127]
	v_mfma_f32_16x16x32_bf16 v[116:119], v[176:179], v[210:213], v[116:119]
	v_mfma_f32_16x16x32_bf16 v[100:103], v[176:179], v[218:221], v[100:103]
	v_mfma_f32_16x16x32_bf16 v[108:111], v[138:141], v[218:221], v[108:111]
	v_mfma_f32_16x16x32_bf16 v[92:95], v[138:141], v[228:231], v[92:95]
	v_mfma_f32_16x16x32_bf16 v[84:87], v[176:179], v[228:231], v[84:87]
	v_mfma_f32_16x16x32_bf16 v[68:71], v[176:179], v[236:239], v[68:71]
	v_mfma_f32_16x16x32_bf16 v[76:79], v[138:141], v[236:239], v[76:79]
	v_mfma_f32_16x16x32_bf16 v[124:127], v[172:175], v[214:217], v[124:127]
	v_mfma_f32_16x16x32_bf16 v[116:119], v[180:183], v[214:217], v[116:119]
	v_mfma_f32_16x16x32_bf16 v[100:103], v[180:183], v[224:227], v[100:103]
	v_mfma_f32_16x16x32_bf16 v[108:111], v[172:175], v[224:227], v[108:111]
	v_mfma_f32_16x16x32_bf16 v[92:95], v[172:175], v[232:235], v[92:95]
	v_mfma_f32_16x16x32_bf16 v[84:87], v[180:183], v[232:235], v[84:87]
	v_mfma_f32_16x16x32_bf16 v[68:71], v[180:183], v[240:243], v[68:71]
	v_mfma_f32_16x16x32_bf16 v[76:79], v[172:175], v[240:243], v[76:79]
	s_setprio 0
	s_setprio 1
	v_mfma_f32_16x16x32_bf16 v[120:123], v[184:187], v[210:213], v[120:123]
	v_mfma_f32_16x16x32_bf16 v[112:115], v[192:195], v[210:213], v[112:115]
	v_mfma_f32_16x16x32_bf16 v[96:99], v[192:195], v[218:221], v[96:99]
	v_mfma_f32_16x16x32_bf16 v[104:107], v[184:187], v[218:221], v[104:107]
	v_mfma_f32_16x16x32_bf16 v[88:91], v[184:187], v[228:231], v[88:91]
	v_mfma_f32_16x16x32_bf16 v[80:83], v[192:195], v[228:231], v[80:83]
	v_mfma_f32_16x16x32_bf16 v[64:67], v[192:195], v[236:239], v[64:67]
	v_mfma_f32_16x16x32_bf16 v[72:75], v[184:187], v[236:239], v[72:75]
	v_mfma_f32_16x16x32_bf16 v[120:123], v[188:191], v[214:217], v[120:123]
	v_mfma_f32_16x16x32_bf16 v[112:115], v[196:199], v[214:217], v[112:115]
	v_mfma_f32_16x16x32_bf16 v[96:99], v[196:199], v[224:227], v[96:99]
	v_mfma_f32_16x16x32_bf16 v[104:107], v[188:191], v[224:227], v[104:107]
	v_mfma_f32_16x16x32_bf16 v[88:91], v[188:191], v[232:235], v[88:91]
	v_mfma_f32_16x16x32_bf16 v[80:83], v[196:199], v[232:235], v[80:83]
	v_mfma_f32_16x16x32_bf16 v[64:67], v[196:199], v[240:243], v[64:67]
	v_mfma_f32_16x16x32_bf16 v[72:75], v[188:191], v[240:243], v[72:75]
	s_setprio 0
	s_barrier
	s_add_i32 s86, s86, s67
	v_lshl_add_u64 v[142:143], s[62:63], 0, v[152:153]
	s_mov_b32 m0, s86
	ds_read_b128 v[210:213], v148 offset:16384
	ds_read_b128 v[214:217], v148 offset:17408
	ds_read_b128 v[218:221], v148 offset:18432
	ds_read_b128 v[224:227], v148 offset:19456
	ds_read_b128 v[228:231], v148 offset:20480
	ds_read_b128 v[232:235], v148 offset:21504
	ds_read_b128 v[236:239], v148 offset:22528
	ds_read_b128 v[240:243], v148 offset:23552
	global_load_lds_dwordx4 v[142:143], off
	s_add_i32 m0, s86, 0x2000
	s_add_u32 s86, s62, 0x40000
	v_lshl_add_u64 v[150:151], s[62:63], 0, v[128:129]
	s_addc_u32 s87, s63, 0
	s_add_i32 s92, s92, s67
	global_load_lds_dwordx4 v[150:151], off
	v_lshl_add_u64 v[244:245], s[86:87], 0, v[152:153]
	s_mov_b32 m0, s92
	v_lshl_add_u64 v[246:247], vcc, 0, v[130:131]
	global_load_lds_dwordx4 v[244:245], off
	v_lshl_add_u64 v[244:245], s[86:87], 0, v[128:129]
	s_add_i32 m0, s92, 0x2000
	s_nop 0
	global_load_lds_dwordx4 v[244:245], off
	v_lshl_add_u64 v[244:245], vcc, 0, v[132:133]
	s_mov_b32 m0, s68
	s_nop 0
	global_load_lds_dwordx4 v[244:245], off
	s_mov_b32 m0, s69
	s_nop 0
	global_load_lds_dwordx4 v[246:247], off
	s_waitcnt vmcnt(8)
	s_waitcnt lgkmcnt(0)
	s_barrier
	s_setprio 1
	s_waitcnt lgkmcnt(0)
	v_mfma_f32_16x16x32_bf16 v[60:63], v[138:141], v[210:213], v[60:63]
	v_mfma_f32_16x16x32_bf16 v[52:55], v[176:179], v[210:213], v[52:55]
	v_mfma_f32_16x16x32_bf16 v[36:39], v[176:179], v[218:221], v[36:39]
	v_mfma_f32_16x16x32_bf16 v[44:47], v[138:141], v[218:221], v[44:47]
	v_mfma_f32_16x16x32_bf16 v[28:31], v[138:141], v[228:231], v[28:31]
	v_mfma_f32_16x16x32_bf16 v[20:23], v[176:179], v[228:231], v[20:23]
	v_mfma_f32_16x16x32_bf16 v[4:7], v[176:179], v[236:239], v[4:7]
	v_mfma_f32_16x16x32_bf16 v[12:15], v[138:141], v[236:239], v[12:15]
	v_mfma_f32_16x16x32_bf16 v[60:63], v[172:175], v[214:217], v[60:63]
	v_mfma_f32_16x16x32_bf16 v[52:55], v[180:183], v[214:217], v[52:55]
	v_mfma_f32_16x16x32_bf16 v[36:39], v[180:183], v[224:227], v[36:39]
	v_mfma_f32_16x16x32_bf16 v[44:47], v[172:175], v[224:227], v[44:47]
	v_mfma_f32_16x16x32_bf16 v[28:31], v[172:175], v[232:235], v[28:31]
	v_mfma_f32_16x16x32_bf16 v[20:23], v[180:183], v[232:235], v[20:23]
	v_mfma_f32_16x16x32_bf16 v[4:7], v[180:183], v[240:243], v[4:7]
	v_mfma_f32_16x16x32_bf16 v[12:15], v[172:175], v[240:243], v[12:15]
	s_setprio 0
	s_setprio 1
	v_mfma_f32_16x16x32_bf16 v[56:59], v[184:187], v[210:213], v[56:59]
	v_mfma_f32_16x16x32_bf16 v[48:51], v[192:195], v[210:213], v[48:51]
	v_mfma_f32_16x16x32_bf16 v[32:35], v[192:195], v[218:221], v[32:35]
	v_mfma_f32_16x16x32_bf16 v[40:43], v[184:187], v[218:221], v[40:43]
	v_mfma_f32_16x16x32_bf16 v[24:27], v[184:187], v[228:231], v[24:27]
	v_mfma_f32_16x16x32_bf16 v[16:19], v[192:195], v[228:231], v[16:19]
	v_mfma_f32_16x16x32_bf16 v[0:3], v[192:195], v[236:239], v[0:3]
	v_mfma_f32_16x16x32_bf16 v[8:11], v[184:187], v[236:239], v[8:11]
	v_mfma_f32_16x16x32_bf16 v[56:59], v[188:191], v[214:217], v[56:59]
	v_mfma_f32_16x16x32_bf16 v[48:51], v[196:199], v[214:217], v[48:51]
	v_mfma_f32_16x16x32_bf16 v[32:35], v[196:199], v[224:227], v[32:35]
	v_mfma_f32_16x16x32_bf16 v[40:43], v[188:191], v[224:227], v[40:43]
	v_mfma_f32_16x16x32_bf16 v[24:27], v[188:191], v[232:235], v[24:27]
	v_mfma_f32_16x16x32_bf16 v[16:19], v[196:199], v[232:235], v[16:19]
	v_mfma_f32_16x16x32_bf16 v[0:3], v[196:199], v[240:243], v[0:3]
	v_mfma_f32_16x16x32_bf16 v[8:11], v[188:191], v[240:243], v[8:11]
	s_setprio 0
	s_barrier
	s_add_i32 s92, 0, 0x18000
	v_add_u32_e32 v149, s92, v145
	s_add_i32 s93, 0, 0x1c000
	ds_read_b128 v[138:141], v149
	ds_read_b128 v[172:175], v149 offset:1024
	ds_read_b128 v[176:179], v149 offset:2048
	ds_read_b128 v[180:183], v149 offset:3072
	v_add_u32_e32 v149, s93, v145
	ds_read_b128 v[184:187], v149
	ds_read_b128 v[188:191], v149 offset:1024
	ds_read_b128 v[192:195], v149 offset:2048
	ds_read_b128 v[196:199], v149 offset:3072
	s_add_u32 s86, vcc_lo, 0x40000
	s_addc_u32 s87, vcc_hi, 0
	s_mov_b32 m0, s74
	v_lshl_add_u64 v[248:249], s[86:87], 0, v[132:133]
	ds_read_b128 v[210:213], v148 offset:32768
	ds_read_b128 v[214:217], v148 offset:33792
	ds_read_b128 v[218:221], v148 offset:34816
	ds_read_b128 v[224:227], v148 offset:35840
	ds_read_b128 v[228:231], v148 offset:36864
	ds_read_b128 v[232:235], v148 offset:37888
	ds_read_b128 v[236:239], v148 offset:38912
	ds_read_b128 v[240:243], v148 offset:39936
	global_load_lds_dwordx4 v[248:249], off
	v_lshl_add_u64 v[248:249], s[86:87], 0, v[130:131]
	s_mov_b32 m0, s75
	s_nop 0
	global_load_lds_dwordx4 v[248:249], off
	s_waitcnt vmcnt(8)
	s_waitcnt lgkmcnt(0)
	s_barrier
	s_setprio 1
	s_waitcnt lgkmcnt(0)
	v_mfma_f32_16x16x32_bf16 v[124:127], v[138:141], v[210:213], v[124:127]
	v_mfma_f32_16x16x32_bf16 v[116:119], v[176:179], v[210:213], v[116:119]
	v_mfma_f32_16x16x32_bf16 v[100:103], v[176:179], v[218:221], v[100:103]
	v_mfma_f32_16x16x32_bf16 v[108:111], v[138:141], v[218:221], v[108:111]
	v_mfma_f32_16x16x32_bf16 v[92:95], v[138:141], v[228:231], v[92:95]
	v_mfma_f32_16x16x32_bf16 v[84:87], v[176:179], v[228:231], v[84:87]
	v_mfma_f32_16x16x32_bf16 v[68:71], v[176:179], v[236:239], v[68:71]
	v_mfma_f32_16x16x32_bf16 v[76:79], v[138:141], v[236:239], v[76:79]
	v_mfma_f32_16x16x32_bf16 v[124:127], v[172:175], v[214:217], v[124:127]
	v_mfma_f32_16x16x32_bf16 v[116:119], v[180:183], v[214:217], v[116:119]
	v_mfma_f32_16x16x32_bf16 v[100:103], v[180:183], v[224:227], v[100:103]
	v_mfma_f32_16x16x32_bf16 v[108:111], v[172:175], v[224:227], v[108:111]
	v_mfma_f32_16x16x32_bf16 v[92:95], v[172:175], v[232:235], v[92:95]
	v_mfma_f32_16x16x32_bf16 v[84:87], v[180:183], v[232:235], v[84:87]
	v_mfma_f32_16x16x32_bf16 v[68:71], v[180:183], v[240:243], v[68:71]
	v_mfma_f32_16x16x32_bf16 v[76:79], v[172:175], v[240:243], v[76:79]
	s_setprio 0
	s_setprio 1
	v_mfma_f32_16x16x32_bf16 v[120:123], v[184:187], v[210:213], v[120:123]
	v_mfma_f32_16x16x32_bf16 v[112:115], v[192:195], v[210:213], v[112:115]
	v_mfma_f32_16x16x32_bf16 v[96:99], v[192:195], v[218:221], v[96:99]
	v_mfma_f32_16x16x32_bf16 v[104:107], v[184:187], v[218:221], v[104:107]
	v_mfma_f32_16x16x32_bf16 v[88:91], v[184:187], v[228:231], v[88:91]
	v_mfma_f32_16x16x32_bf16 v[80:83], v[192:195], v[228:231], v[80:83]
	v_mfma_f32_16x16x32_bf16 v[64:67], v[192:195], v[236:239], v[64:67]
	v_mfma_f32_16x16x32_bf16 v[72:75], v[184:187], v[236:239], v[72:75]
	v_mfma_f32_16x16x32_bf16 v[120:123], v[188:191], v[214:217], v[120:123]
	v_mfma_f32_16x16x32_bf16 v[112:115], v[196:199], v[214:217], v[112:115]
	v_mfma_f32_16x16x32_bf16 v[96:99], v[196:199], v[224:227], v[96:99]
	v_mfma_f32_16x16x32_bf16 v[104:107], v[188:191], v[224:227], v[104:107]
	v_mfma_f32_16x16x32_bf16 v[88:91], v[188:191], v[232:235], v[88:91]
	v_mfma_f32_16x16x32_bf16 v[80:83], v[196:199], v[232:235], v[80:83]
	v_mfma_f32_16x16x32_bf16 v[64:67], v[196:199], v[240:243], v[64:67]
	v_mfma_f32_16x16x32_bf16 v[72:75], v[188:191], v[240:243], v[72:75]
	s_setprio 0
	s_barrier
	s_add_i32 s86, s92, s67
	v_lshl_add_u64 v[142:143], v[142:143], 0, s[22:23]
	s_mov_b32 m0, s86
	ds_read_b128 v[210:213], v148 offset:49152
	ds_read_b128 v[214:217], v148 offset:50176
	ds_read_b128 v[218:221], v148 offset:51200
	ds_read_b128 v[224:227], v148 offset:52224
	ds_read_b128 v[228:231], v148 offset:53248
	ds_read_b128 v[232:235], v148 offset:54272
	ds_read_b128 v[236:239], v148 offset:55296
	ds_read_b128 v[240:243], v148 offset:56320
	global_load_lds_dwordx4 v[142:143], off
	s_add_i32 m0, s86, 0x2000
	s_add_u32 s62, s62, 0x40080
	v_lshl_add_u64 v[142:143], v[150:151], 0, s[22:23]
	s_addc_u32 s63, s63, 0
	s_add_i32 s86, s93, s67
	global_load_lds_dwordx4 v[142:143], off
	v_lshl_add_u64 v[142:143], s[62:63], 0, v[152:153]
	s_mov_b32 m0, s86
	s_nop 0
	global_load_lds_dwordx4 v[142:143], off
	v_lshl_add_u64 v[142:143], s[62:63], 0, v[128:129]
	s_add_i32 m0, s86, 0x2000
	s_nop 0
	global_load_lds_dwordx4 v[142:143], off
	v_lshl_add_u64 v[142:143], v[244:245], 0, s[22:23]
	s_mov_b32 m0, s77
	s_nop 0
	global_load_lds_dwordx4 v[142:143], off
	v_lshl_add_u64 v[142:143], v[246:247], 0, s[22:23]
	s_mov_b32 m0, s78
	s_nop 0
	global_load_lds_dwordx4 v[142:143], off
	s_waitcnt vmcnt(8)
	s_waitcnt lgkmcnt(0)
	s_barrier
	s_setprio 1
	s_waitcnt lgkmcnt(0)
	v_mfma_f32_16x16x32_bf16 v[60:63], v[138:141], v[210:213], v[60:63]
	v_mfma_f32_16x16x32_bf16 v[52:55], v[176:179], v[210:213], v[52:55]
	v_mfma_f32_16x16x32_bf16 v[36:39], v[176:179], v[218:221], v[36:39]
	v_mfma_f32_16x16x32_bf16 v[44:47], v[138:141], v[218:221], v[44:47]
	v_mfma_f32_16x16x32_bf16 v[28:31], v[138:141], v[228:231], v[28:31]
	v_mfma_f32_16x16x32_bf16 v[20:23], v[176:179], v[228:231], v[20:23]
	v_mfma_f32_16x16x32_bf16 v[4:7], v[176:179], v[236:239], v[4:7]
	v_mfma_f32_16x16x32_bf16 v[12:15], v[138:141], v[236:239], v[12:15]
	v_mfma_f32_16x16x32_bf16 v[60:63], v[172:175], v[214:217], v[60:63]
	v_mfma_f32_16x16x32_bf16 v[52:55], v[180:183], v[214:217], v[52:55]
	v_mfma_f32_16x16x32_bf16 v[36:39], v[180:183], v[224:227], v[36:39]
	v_mfma_f32_16x16x32_bf16 v[44:47], v[172:175], v[224:227], v[44:47]
	v_mfma_f32_16x16x32_bf16 v[28:31], v[172:175], v[232:235], v[28:31]
	v_mfma_f32_16x16x32_bf16 v[20:23], v[180:183], v[232:235], v[20:23]
	v_mfma_f32_16x16x32_bf16 v[4:7], v[180:183], v[240:243], v[4:7]
	v_mfma_f32_16x16x32_bf16 v[12:15], v[172:175], v[240:243], v[12:15]
	s_setprio 0
	s_setprio 1
	v_mfma_f32_16x16x32_bf16 v[56:59], v[184:187], v[210:213], v[56:59]
	v_mfma_f32_16x16x32_bf16 v[48:51], v[192:195], v[210:213], v[48:51]
	v_mfma_f32_16x16x32_bf16 v[32:35], v[192:195], v[218:221], v[32:35]
	v_mfma_f32_16x16x32_bf16 v[40:43], v[184:187], v[218:221], v[40:43]
	v_mfma_f32_16x16x32_bf16 v[24:27], v[184:187], v[228:231], v[24:27]
	v_mfma_f32_16x16x32_bf16 v[16:19], v[192:195], v[228:231], v[16:19]
	v_mfma_f32_16x16x32_bf16 v[0:3], v[192:195], v[236:239], v[0:3]
	v_mfma_f32_16x16x32_bf16 v[8:11], v[184:187], v[236:239], v[8:11]
	v_mfma_f32_16x16x32_bf16 v[56:59], v[188:191], v[214:217], v[56:59]
	v_mfma_f32_16x16x32_bf16 v[48:51], v[196:199], v[214:217], v[48:51]
	v_mfma_f32_16x16x32_bf16 v[32:35], v[196:199], v[224:227], v[32:35]
	v_mfma_f32_16x16x32_bf16 v[40:43], v[188:191], v[224:227], v[40:43]
	v_mfma_f32_16x16x32_bf16 v[24:27], v[188:191], v[232:235], v[24:27]
	v_mfma_f32_16x16x32_bf16 v[16:19], v[196:199], v[232:235], v[16:19]
	v_mfma_f32_16x16x32_bf16 v[0:3], v[196:199], v[240:243], v[0:3]
	v_mfma_f32_16x16x32_bf16 v[8:11], v[188:191], v[240:243], v[8:11]
	s_setprio 0
	s_barrier
	s_add_i32 s85, s85, 2
	s_add_u32 s89, s89, 0x100
	s_addc_u32 s84, s84, 0
	s_add_u32 s60, s60, 0x100
	s_addc_u32 s61, s61, 0
	s_cmp_gt_u32 s85, 13
	s_cbranch_scc0 .LBB0_180
	s_and_b64 vcc, exec, s[18:19]
	s_cbranch_vccz .LBB0_183
	s_barrier

.LBB0_281:
	s_add_u32 vcc_lo, s60, 0x100
	s_addc_u32 vcc_hi, s61, 0
	s_add_i32 s87, 0, 0x10000
	s_cmp_eq_u32 s86, 40
	s_cselect_b32 s67, s51, vcc_hi
	s_cselect_b32 s66, s50, vcc_lo
	s_cselect_b32 s19, s45, s85
	s_cselect_b32 s18, s44, s84
	s_add_i32 s92, 0, 0x14000
	v_add_u32_e32 v140, s87, v210
	v_add_u32_e32 v186, s92, v210
	ds_read_b128 v[128:131], v140
	ds_read_b128 v[132:135], v140 offset:1024
	ds_read_b128 v[136:139], v140 offset:2048
	ds_read_b128 v[140:143], v140 offset:3072
	ds_read_b128 v[144:147], v186
	ds_read_b128 v[148:151], v186 offset:1024
	ds_read_b128 v[182:185], v186 offset:2048
	ds_read_b128 v[186:189], v186 offset:3072
	v_lshl_add_u64 v[198:199], s[60:61], 0, v[180:181]
	s_add_i32 m0, s69, 0xc000
	ds_read_b128 v[190:193], v212
	ds_read_b128 v[194:197], v212 offset:1024
	ds_read_b128 v[214:217], v212 offset:2048
	ds_read_b128 v[218:221], v212 offset:3072
	ds_read_b128 v[224:227], v212 offset:4096
	ds_read_b128 v[228:231], v212 offset:5120
	ds_read_b128 v[232:235], v212 offset:6144
	ds_read_b128 v[236:239], v212 offset:7168
	global_load_lds_dwordx4 v[198:199], off
	v_lshl_add_u64 v[198:199], s[60:61], 0, v[178:179]
	s_add_i32 m0, s69, 0xe000
	s_nop 0
	global_load_lds_dwordx4 v[198:199], off
	s_waitcnt vmcnt(8)
	s_waitcnt lgkmcnt(0)
	s_barrier
	s_setprio 1
	s_waitcnt lgkmcnt(0)
	v_mfma_f32_16x16x32_bf16 v[124:127], v[128:131], v[190:193], v[124:127]
	v_mfma_f32_16x16x32_bf16 v[120:123], v[136:139], v[190:193], v[120:123]
	v_mfma_f32_16x16x32_bf16 v[104:107], v[136:139], v[214:217], v[104:107]
	v_mfma_f32_16x16x32_bf16 v[108:111], v[128:131], v[214:217], v[108:111]
	v_mfma_f32_16x16x32_bf16 v[92:95], v[128:131], v[224:227], v[92:95]
	v_mfma_f32_16x16x32_bf16 v[88:91], v[136:139], v[224:227], v[88:91]
	v_mfma_f32_16x16x32_bf16 v[72:75], v[136:139], v[232:235], v[72:75]
	v_mfma_f32_16x16x32_bf16 v[76:79], v[128:131], v[232:235], v[76:79]
	v_mfma_f32_16x16x32_bf16 v[124:127], v[132:135], v[194:197], v[124:127]
	v_mfma_f32_16x16x32_bf16 v[120:123], v[140:143], v[194:197], v[120:123]
	v_mfma_f32_16x16x32_bf16 v[104:107], v[140:143], v[218:221], v[104:107]
	v_mfma_f32_16x16x32_bf16 v[108:111], v[132:135], v[218:221], v[108:111]
	v_mfma_f32_16x16x32_bf16 v[92:95], v[132:135], v[228:231], v[92:95]
	v_mfma_f32_16x16x32_bf16 v[88:91], v[140:143], v[228:231], v[88:91]
	v_mfma_f32_16x16x32_bf16 v[72:75], v[140:143], v[236:239], v[72:75]
	v_mfma_f32_16x16x32_bf16 v[76:79], v[132:135], v[236:239], v[76:79]
	s_setprio 0
	s_setprio 1
	v_mfma_f32_16x16x32_bf16 v[116:119], v[144:147], v[190:193], v[116:119]
	v_mfma_f32_16x16x32_bf16 v[112:115], v[182:185], v[190:193], v[112:115]
	v_mfma_f32_16x16x32_bf16 v[96:99], v[182:185], v[214:217], v[96:99]
	v_mfma_f32_16x16x32_bf16 v[100:103], v[144:147], v[214:217], v[100:103]
	v_mfma_f32_16x16x32_bf16 v[84:87], v[144:147], v[224:227], v[84:87]
	v_mfma_f32_16x16x32_bf16 v[80:83], v[182:185], v[224:227], v[80:83]
	v_mfma_f32_16x16x32_bf16 v[64:67], v[182:185], v[232:235], v[64:67]
	v_mfma_f32_16x16x32_bf16 v[68:71], v[144:147], v[232:235], v[68:71]
	v_mfma_f32_16x16x32_bf16 v[116:119], v[148:151], v[194:197], v[116:119]
	v_mfma_f32_16x16x32_bf16 v[112:115], v[186:189], v[194:197], v[112:115]
	v_mfma_f32_16x16x32_bf16 v[96:99], v[186:189], v[218:221], v[96:99]
	v_mfma_f32_16x16x32_bf16 v[100:103], v[148:151], v[218:221], v[100:103]
	v_mfma_f32_16x16x32_bf16 v[84:87], v[148:151], v[228:231], v[84:87]
	v_mfma_f32_16x16x32_bf16 v[80:83], v[186:189], v[228:231], v[80:83]
	v_mfma_f32_16x16x32_bf16 v[64:67], v[186:189], v[236:239], v[64:67]
	v_mfma_f32_16x16x32_bf16 v[68:71], v[148:151], v[236:239], v[68:71]
	s_setprio 0
	s_barrier
	s_add_i32 s60, s87, s68
	v_lshl_add_u64 v[198:199], s[18:19], 0, v[152:153]
	s_mov_b32 m0, s60
	ds_read_b128 v[190:193], v212 offset:16384
	ds_read_b128 v[194:197], v212 offset:17408
	ds_read_b128 v[214:217], v212 offset:18432
	ds_read_b128 v[218:221], v212 offset:19456
	ds_read_b128 v[224:227], v212 offset:20480
	ds_read_b128 v[228:231], v212 offset:21504
	ds_read_b128 v[232:235], v212 offset:22528
	ds_read_b128 v[236:239], v212 offset:23552
	global_load_lds_dwordx4 v[198:199], off
	s_add_i32 m0, s60, 0x2000
	s_add_u32 s60, s18, 0xb0000
	v_lshl_add_u64 v[240:241], s[18:19], 0, v[172:173]
	s_addc_u32 s61, s19, 0
	s_add_i32 s87, s92, s68
	global_load_lds_dwordx4 v[240:241], off
	v_lshl_add_u64 v[242:243], s[60:61], 0, v[152:153]
	s_mov_b32 m0, s87
	v_lshl_add_u64 v[244:245], s[66:67], 0, v[174:175]
	global_load_lds_dwordx4 v[242:243], off
	v_lshl_add_u64 v[242:243], s[60:61], 0, v[172:173]
	s_add_i32 m0, s87, 0x2000
	s_nop 0
	global_load_lds_dwordx4 v[242:243], off
	v_lshl_add_u64 v[242:243], s[66:67], 0, v[176:177]
	s_mov_b32 m0, s69
	s_nop 0
	global_load_lds_dwordx4 v[242:243], off
	s_mov_b32 m0, s74
	s_nop 0
	global_load_lds_dwordx4 v[244:245], off
	s_waitcnt vmcnt(8)
	s_waitcnt lgkmcnt(0)
	s_barrier
	s_setprio 1
	s_waitcnt lgkmcnt(0)
	v_mfma_f32_16x16x32_bf16 v[60:63], v[128:131], v[190:193], v[60:63]
	v_mfma_f32_16x16x32_bf16 v[56:59], v[136:139], v[190:193], v[56:59]
	v_mfma_f32_16x16x32_bf16 v[40:43], v[136:139], v[214:217], v[40:43]
	v_mfma_f32_16x16x32_bf16 v[44:47], v[128:131], v[214:217], v[44:47]
	v_mfma_f32_16x16x32_bf16 v[28:31], v[128:131], v[224:227], v[28:31]
	v_mfma_f32_16x16x32_bf16 v[24:27], v[136:139], v[224:227], v[24:27]
	v_mfma_f32_16x16x32_bf16 v[8:11], v[136:139], v[232:235], v[8:11]
	v_mfma_f32_16x16x32_bf16 v[12:15], v[128:131], v[232:235], v[12:15]
	v_mfma_f32_16x16x32_bf16 v[60:63], v[132:135], v[194:197], v[60:63]
	v_mfma_f32_16x16x32_bf16 v[56:59], v[140:143], v[194:197], v[56:59]
	v_mfma_f32_16x16x32_bf16 v[40:43], v[140:143], v[218:221], v[40:43]
	v_mfma_f32_16x16x32_bf16 v[44:47], v[132:135], v[218:221], v[44:47]
	v_mfma_f32_16x16x32_bf16 v[28:31], v[132:135], v[228:231], v[28:31]
	v_mfma_f32_16x16x32_bf16 v[24:27], v[140:143], v[228:231], v[24:27]
	v_mfma_f32_16x16x32_bf16 v[8:11], v[140:143], v[236:239], v[8:11]
	v_mfma_f32_16x16x32_bf16 v[12:15], v[132:135], v[236:239], v[12:15]
	s_setprio 0
	s_setprio 1
	v_mfma_f32_16x16x32_bf16 v[52:55], v[144:147], v[190:193], v[52:55]
	v_mfma_f32_16x16x32_bf16 v[48:51], v[182:185], v[190:193], v[48:51]
	v_mfma_f32_16x16x32_bf16 v[32:35], v[182:185], v[214:217], v[32:35]
	v_mfma_f32_16x16x32_bf16 v[36:39], v[144:147], v[214:217], v[36:39]
	v_mfma_f32_16x16x32_bf16 v[20:23], v[144:147], v[224:227], v[20:23]
	v_mfma_f32_16x16x32_bf16 v[16:19], v[182:185], v[224:227], v[16:19]
	v_mfma_f32_16x16x32_bf16 v[0:3], v[182:185], v[232:235], v[0:3]
	v_mfma_f32_16x16x32_bf16 v[4:7], v[144:147], v[232:235], v[4:7]
	v_mfma_f32_16x16x32_bf16 v[52:55], v[148:151], v[194:197], v[52:55]
	v_mfma_f32_16x16x32_bf16 v[48:51], v[186:189], v[194:197], v[48:51]
	v_mfma_f32_16x16x32_bf16 v[32:35], v[186:189], v[218:221], v[32:35]
	v_mfma_f32_16x16x32_bf16 v[36:39], v[148:151], v[218:221], v[36:39]
	v_mfma_f32_16x16x32_bf16 v[20:23], v[148:151], v[228:231], v[20:23]
	v_mfma_f32_16x16x32_bf16 v[16:19], v[186:189], v[228:231], v[16:19]
	v_mfma_f32_16x16x32_bf16 v[0:3], v[186:189], v[236:239], v[0:3]
	v_mfma_f32_16x16x32_bf16 v[4:7], v[148:151], v[236:239], v[4:7]
	s_setprio 0
	s_barrier
	s_add_i32 s87, 0, 0x18000
	s_add_i32 s92, 0, 0x1c000
	v_add_u32_e32 v140, s87, v210
	v_add_u32_e32 v186, s92, v210
	ds_read_b128 v[128:131], v140
	ds_read_b128 v[132:135], v140 offset:1024
	ds_read_b128 v[136:139], v140 offset:2048
	ds_read_b128 v[140:143], v140 offset:3072
	ds_read_b128 v[144:147], v186
	ds_read_b128 v[148:151], v186 offset:1024
	ds_read_b128 v[182:185], v186 offset:2048
	ds_read_b128 v[186:189], v186 offset:3072
	s_add_u32 s60, s66, 0xb0000
	s_addc_u32 s61, s67, 0
	s_mov_b32 m0, s75
	v_lshl_add_u64 v[246:247], s[60:61], 0, v[176:177]
	ds_read_b128 v[190:193], v212 offset:32768
	ds_read_b128 v[194:197], v212 offset:33792
	ds_read_b128 v[214:217], v212 offset:34816
	ds_read_b128 v[218:221], v212 offset:35840
	ds_read_b128 v[224:227], v212 offset:36864
	ds_read_b128 v[228:231], v212 offset:37888
	ds_read_b128 v[232:235], v212 offset:38912
	ds_read_b128 v[236:239], v212 offset:39936
	global_load_lds_dwordx4 v[246:247], off
	v_lshl_add_u64 v[246:247], s[60:61], 0, v[174:175]
	s_mov_b32 m0, s76
	s_nop 0
	global_load_lds_dwordx4 v[246:247], off
	s_waitcnt vmcnt(8)
	s_waitcnt lgkmcnt(0)
	s_barrier
	s_setprio 1
	s_waitcnt lgkmcnt(0)
	v_mfma_f32_16x16x32_bf16 v[124:127], v[128:131], v[190:193], v[124:127]
	v_mfma_f32_16x16x32_bf16 v[120:123], v[136:139], v[190:193], v[120:123]
	v_mfma_f32_16x16x32_bf16 v[104:107], v[136:139], v[214:217], v[104:107]
	v_mfma_f32_16x16x32_bf16 v[108:111], v[128:131], v[214:217], v[108:111]
	v_mfma_f32_16x16x32_bf16 v[92:95], v[128:131], v[224:227], v[92:95]
	v_mfma_f32_16x16x32_bf16 v[88:91], v[136:139], v[224:227], v[88:91]
	v_mfma_f32_16x16x32_bf16 v[72:75], v[136:139], v[232:235], v[72:75]
	v_mfma_f32_16x16x32_bf16 v[76:79], v[128:131], v[232:235], v[76:79]
	v_mfma_f32_16x16x32_bf16 v[124:127], v[132:135], v[194:197], v[124:127]
	v_mfma_f32_16x16x32_bf16 v[120:123], v[140:143], v[194:197], v[120:123]
	v_mfma_f32_16x16x32_bf16 v[104:107], v[140:143], v[218:221], v[104:107]
	v_mfma_f32_16x16x32_bf16 v[108:111], v[132:135], v[218:221], v[108:111]
	v_mfma_f32_16x16x32_bf16 v[92:95], v[132:135], v[228:231], v[92:95]
	v_mfma_f32_16x16x32_bf16 v[88:91], v[140:143], v[228:231], v[88:91]
	v_mfma_f32_16x16x32_bf16 v[72:75], v[140:143], v[236:239], v[72:75]
	v_mfma_f32_16x16x32_bf16 v[76:79], v[132:135], v[236:239], v[76:79]
	s_setprio 0
	s_setprio 1
	v_mfma_f32_16x16x32_bf16 v[116:119], v[144:147], v[190:193], v[116:119]
	v_mfma_f32_16x16x32_bf16 v[112:115], v[182:185], v[190:193], v[112:115]
	v_mfma_f32_16x16x32_bf16 v[96:99], v[182:185], v[214:217], v[96:99]
	v_mfma_f32_16x16x32_bf16 v[100:103], v[144:147], v[214:217], v[100:103]
	v_mfma_f32_16x16x32_bf16 v[84:87], v[144:147], v[224:227], v[84:87]
	v_mfma_f32_16x16x32_bf16 v[80:83], v[182:185], v[224:227], v[80:83]
	v_mfma_f32_16x16x32_bf16 v[64:67], v[182:185], v[232:235], v[64:67]
	v_mfma_f32_16x16x32_bf16 v[68:71], v[144:147], v[232:235], v[68:71]
	v_mfma_f32_16x16x32_bf16 v[116:119], v[148:151], v[194:197], v[116:119]
	v_mfma_f32_16x16x32_bf16 v[112:115], v[186:189], v[194:197], v[112:115]
	v_mfma_f32_16x16x32_bf16 v[96:99], v[186:189], v[218:221], v[96:99]
	v_mfma_f32_16x16x32_bf16 v[100:103], v[148:151], v[218:221], v[100:103]
	v_mfma_f32_16x16x32_bf16 v[84:87], v[148:151], v[228:231], v[84:87]
	v_mfma_f32_16x16x32_bf16 v[80:83], v[186:189], v[228:231], v[80:83]
	v_mfma_f32_16x16x32_bf16 v[64:67], v[186:189], v[236:239], v[64:67]
	v_mfma_f32_16x16x32_bf16 v[68:71], v[148:151], v[236:239], v[68:71]
	s_setprio 0
	s_barrier
	s_add_i32 s60, s87, s68
	v_lshl_add_u64 v[198:199], v[198:199], 0, s[22:23]
	s_mov_b32 m0, s60
	ds_read_b128 v[190:193], v212 offset:49152
	ds_read_b128 v[194:197], v212 offset:50176
	ds_read_b128 v[214:217], v212 offset:51200
	ds_read_b128 v[218:221], v212 offset:52224
	ds_read_b128 v[224:227], v212 offset:53248
	ds_read_b128 v[228:231], v212 offset:54272
	ds_read_b128 v[232:235], v212 offset:55296
	ds_read_b128 v[236:239], v212 offset:56320
	global_load_lds_dwordx4 v[198:199], off
	s_add_i32 m0, s60, 0x2000
	s_add_u32 s18, s18, 0xb0080
	v_lshl_add_u64 v[198:199], v[240:241], 0, s[22:23]
	s_addc_u32 s19, s19, 0
	s_add_i32 s60, s92, s68
	global_load_lds_dwordx4 v[198:199], off
	v_lshl_add_u64 v[198:199], s[18:19], 0, v[152:153]
	s_mov_b32 m0, s60
	s_nop 0
	global_load_lds_dwordx4 v[198:199], off
	v_lshl_add_u64 v[198:199], s[18:19], 0, v[172:173]
	s_add_i32 m0, s60, 0x2000
	s_nop 0
	global_load_lds_dwordx4 v[198:199], off
	v_lshl_add_u64 v[198:199], v[242:243], 0, s[22:23]
	s_mov_b32 m0, s79
	s_nop 0
	global_load_lds_dwordx4 v[198:199], off
	v_lshl_add_u64 v[198:199], v[244:245], 0, s[22:23]
	s_mov_b32 m0, s80
	s_nop 0
	global_load_lds_dwordx4 v[198:199], off
	s_waitcnt vmcnt(8)
	s_waitcnt lgkmcnt(0)
	s_barrier
	s_setprio 1
	s_waitcnt lgkmcnt(0)
	v_mfma_f32_16x16x32_bf16 v[60:63], v[128:131], v[190:193], v[60:63]
	v_mfma_f32_16x16x32_bf16 v[56:59], v[136:139], v[190:193], v[56:59]
	v_mfma_f32_16x16x32_bf16 v[40:43], v[136:139], v[214:217], v[40:43]
	v_mfma_f32_16x16x32_bf16 v[44:47], v[128:131], v[214:217], v[44:47]
	v_mfma_f32_16x16x32_bf16 v[28:31], v[128:131], v[224:227], v[28:31]
	v_mfma_f32_16x16x32_bf16 v[24:27], v[136:139], v[224:227], v[24:27]
	v_mfma_f32_16x16x32_bf16 v[8:11], v[136:139], v[232:235], v[8:11]
	v_mfma_f32_16x16x32_bf16 v[12:15], v[128:131], v[232:235], v[12:15]
	v_mfma_f32_16x16x32_bf16 v[60:63], v[132:135], v[194:197], v[60:63]
	v_mfma_f32_16x16x32_bf16 v[56:59], v[140:143], v[194:197], v[56:59]
	v_mfma_f32_16x16x32_bf16 v[40:43], v[140:143], v[218:221], v[40:43]
	v_mfma_f32_16x16x32_bf16 v[44:47], v[132:135], v[218:221], v[44:47]
	v_mfma_f32_16x16x32_bf16 v[28:31], v[132:135], v[228:231], v[28:31]
	v_mfma_f32_16x16x32_bf16 v[24:27], v[140:143], v[228:231], v[24:27]
	v_mfma_f32_16x16x32_bf16 v[8:11], v[140:143], v[236:239], v[8:11]
	v_mfma_f32_16x16x32_bf16 v[12:15], v[132:135], v[236:239], v[12:15]
	s_setprio 0
	s_setprio 1
	v_mfma_f32_16x16x32_bf16 v[52:55], v[144:147], v[190:193], v[52:55]
	v_mfma_f32_16x16x32_bf16 v[48:51], v[182:185], v[190:193], v[48:51]
	v_mfma_f32_16x16x32_bf16 v[32:35], v[182:185], v[214:217], v[32:35]
	v_mfma_f32_16x16x32_bf16 v[36:39], v[144:147], v[214:217], v[36:39]
	v_mfma_f32_16x16x32_bf16 v[20:23], v[144:147], v[224:227], v[20:23]
	v_mfma_f32_16x16x32_bf16 v[16:19], v[182:185], v[224:227], v[16:19]
	v_mfma_f32_16x16x32_bf16 v[0:3], v[182:185], v[232:235], v[0:3]
	v_mfma_f32_16x16x32_bf16 v[4:7], v[144:147], v[232:235], v[4:7]
	v_mfma_f32_16x16x32_bf16 v[52:55], v[148:151], v[194:197], v[52:55]
	v_mfma_f32_16x16x32_bf16 v[48:51], v[186:189], v[194:197], v[48:51]
	v_mfma_f32_16x16x32_bf16 v[32:35], v[186:189], v[218:221], v[32:35]
	v_mfma_f32_16x16x32_bf16 v[36:39], v[148:151], v[218:221], v[36:39]
	v_mfma_f32_16x16x32_bf16 v[20:23], v[148:151], v[228:231], v[20:23]
	v_mfma_f32_16x16x32_bf16 v[16:19], v[186:189], v[228:231], v[16:19]
	v_mfma_f32_16x16x32_bf16 v[0:3], v[186:189], v[236:239], v[0:3]
	v_mfma_f32_16x16x32_bf16 v[4:7], v[148:151], v[236:239], v[4:7]
	s_setprio 0
	s_barrier
	s_add_i32 s86, s86, 2
	s_add_u32 s84, s84, 0x100
	s_addc_u32 s85, s85, 0
	s_cmp_gt_u32 s86, 41
	s_mov_b64 s[60:61], vcc
	s_cbranch_scc0 .LBB0_281
	s_and_b64 vcc, exec, s[10:11]
	s_cbranch_vccz .LBB0_284
	s_barrier

.LBB0_419:
	s_add_u32 s44, s48, 0xfffc0080
	s_addc_u32 s45, s49, -1
	s_add_i32 s83, 0, 0x10000
	s_cmp_eq_u32 s82, 12
	s_cselect_b32 s63, s21, s45
	s_cselect_b32 s62, s78, s44
	s_cselect_b32 s45, s19, s81
	s_cselect_b32 s44, s79, s80
	s_add_i32 s86, 0, 0x14000
	v_add_u32_e32 v88, s83, v185
	v_add_u32_e32 v182, s86, v185
	ds_read_b128 v[72:75], v88
	ds_read_b128 v[76:79], v88 offset:1024
	ds_read_b128 v[80:83], v88 offset:2048
	ds_read_b128 v[88:91], v88 offset:3072
	ds_read_b128 v[174:177], v182
	ds_read_b128 v[178:181], v182 offset:1024
	ds_read_b128 v[190:193], v182 offset:2048
	ds_read_b128 v[194:197], v182 offset:3072
	v_lshl_add_u64 v[182:183], s[48:49], 0, v[172:173]
	s_add_i32 m0, s59, 0xc000
	ds_read_b128 v[210:213], v188
	ds_read_b128 v[214:217], v188 offset:1024
	ds_read_b128 v[218:221], v188 offset:2048
	ds_read_b128 v[224:227], v188 offset:3072
	ds_read_b128 v[228:231], v188 offset:4096
	ds_read_b128 v[232:235], v188 offset:5120
	ds_read_b128 v[236:239], v188 offset:6144
	ds_read_b128 v[240:243], v188 offset:7168
	global_load_lds_dwordx4 v[182:183], off
	v_lshl_add_u64 v[182:183], s[48:49], 0, v[150:151]
	s_add_i32 m0, s59, 0xe000
	s_nop 0
	global_load_lds_dwordx4 v[182:183], off
	s_waitcnt vmcnt(8)
	s_waitcnt lgkmcnt(0)
	s_barrier
	s_setprio 1
	s_waitcnt lgkmcnt(0)
	v_mfma_f32_16x16x32_bf16 v[140:143], v[72:75], v[210:213], v[140:143]
	v_mfma_f32_16x16x32_bf16 v[136:139], v[80:83], v[210:213], v[136:139]
	v_mfma_f32_16x16x32_bf16 v[120:123], v[80:83], v[218:221], v[120:123]
	v_mfma_f32_16x16x32_bf16 v[124:127], v[72:75], v[218:221], v[124:127]
	v_mfma_f32_16x16x32_bf16 v[108:111], v[72:75], v[228:231], v[108:111]
	v_mfma_f32_16x16x32_bf16 v[104:107], v[80:83], v[228:231], v[104:107]
	v_mfma_f32_16x16x32_bf16 v[84:87], v[80:83], v[236:239], v[84:87]
	v_mfma_f32_16x16x32_bf16 v[92:95], v[72:75], v[236:239], v[92:95]
	v_mfma_f32_16x16x32_bf16 v[140:143], v[76:79], v[214:217], v[140:143]
	v_mfma_f32_16x16x32_bf16 v[136:139], v[88:91], v[214:217], v[136:139]
	v_mfma_f32_16x16x32_bf16 v[120:123], v[88:91], v[224:227], v[120:123]
	v_mfma_f32_16x16x32_bf16 v[124:127], v[76:79], v[224:227], v[124:127]
	v_mfma_f32_16x16x32_bf16 v[108:111], v[76:79], v[232:235], v[108:111]
	v_mfma_f32_16x16x32_bf16 v[104:107], v[88:91], v[232:235], v[104:107]
	v_mfma_f32_16x16x32_bf16 v[84:87], v[88:91], v[240:243], v[84:87]
	v_mfma_f32_16x16x32_bf16 v[92:95], v[76:79], v[240:243], v[92:95]
	s_setprio 0
	s_setprio 1
	v_mfma_f32_16x16x32_bf16 v[132:135], v[174:177], v[210:213], v[132:135]
	v_mfma_f32_16x16x32_bf16 v[128:131], v[190:193], v[210:213], v[128:131]
	v_mfma_f32_16x16x32_bf16 v[112:115], v[190:193], v[218:221], v[112:115]
	v_mfma_f32_16x16x32_bf16 v[116:119], v[174:177], v[218:221], v[116:119]
	v_mfma_f32_16x16x32_bf16 v[100:103], v[174:177], v[228:231], v[100:103]
	v_mfma_f32_16x16x32_bf16 v[96:99], v[190:193], v[228:231], v[96:99]
	v_mfma_f32_16x16x32_bf16 v[64:67], v[190:193], v[236:239], v[64:67]
	v_mfma_f32_16x16x32_bf16 v[68:71], v[174:177], v[236:239], v[68:71]
	v_mfma_f32_16x16x32_bf16 v[132:135], v[178:181], v[214:217], v[132:135]
	v_mfma_f32_16x16x32_bf16 v[128:131], v[194:197], v[214:217], v[128:131]
	v_mfma_f32_16x16x32_bf16 v[112:115], v[194:197], v[224:227], v[112:115]
	v_mfma_f32_16x16x32_bf16 v[116:119], v[178:181], v[224:227], v[116:119]
	v_mfma_f32_16x16x32_bf16 v[100:103], v[178:181], v[232:235], v[100:103]
	v_mfma_f32_16x16x32_bf16 v[96:99], v[194:197], v[232:235], v[96:99]
	v_mfma_f32_16x16x32_bf16 v[64:67], v[194:197], v[240:243], v[64:67]
	v_mfma_f32_16x16x32_bf16 v[68:71], v[178:181], v[240:243], v[68:71]
	s_setprio 0
	s_barrier
	s_add_i32 s83, s83, s8
	v_lshl_add_u64 v[182:183], s[44:45], 0, v[152:153]
	s_mov_b32 m0, s83
	ds_read_b128 v[210:213], v188 offset:16384
	ds_read_b128 v[214:217], v188 offset:17408
	ds_read_b128 v[218:221], v188 offset:18432
	ds_read_b128 v[224:227], v188 offset:19456
	ds_read_b128 v[228:231], v188 offset:20480
	ds_read_b128 v[232:235], v188 offset:21504
	ds_read_b128 v[236:239], v188 offset:22528
	ds_read_b128 v[240:243], v188 offset:23552
	global_load_lds_dwordx4 v[182:183], off
	s_add_i32 m0, s83, 0x2000
	s_add_u32 s84, s44, 0x40000
	v_lshl_add_u64 v[198:199], s[44:45], 0, v[144:145]
	s_addc_u32 s85, s45, 0
	s_add_i32 s83, s86, s8
	global_load_lds_dwordx4 v[198:199], off
	v_lshl_add_u64 v[244:245], s[84:85], 0, v[152:153]
	s_mov_b32 m0, s83
	v_lshl_add_u64 v[246:247], s[62:63], 0, v[146:147]
	global_load_lds_dwordx4 v[244:245], off
	v_lshl_add_u64 v[244:245], s[84:85], 0, v[144:145]
	s_add_i32 m0, s83, 0x2000
	s_nop 0
	global_load_lds_dwordx4 v[244:245], off
	v_lshl_add_u64 v[244:245], s[62:63], 0, v[148:149]
	s_mov_b32 m0, s59
	s_nop 0
	global_load_lds_dwordx4 v[244:245], off
	s_mov_b32 m0, s66
	s_nop 0
	global_load_lds_dwordx4 v[246:247], off
	s_waitcnt vmcnt(8)
	s_waitcnt lgkmcnt(0)
	s_barrier
	s_setprio 1
	s_waitcnt lgkmcnt(0)
	v_mfma_f32_16x16x32_bf16 v[60:63], v[72:75], v[210:213], v[60:63]
	v_mfma_f32_16x16x32_bf16 v[56:59], v[80:83], v[210:213], v[56:59]
	v_mfma_f32_16x16x32_bf16 v[40:43], v[80:83], v[218:221], v[40:43]
	v_mfma_f32_16x16x32_bf16 v[44:47], v[72:75], v[218:221], v[44:47]
	v_mfma_f32_16x16x32_bf16 v[28:31], v[72:75], v[228:231], v[28:31]
	v_mfma_f32_16x16x32_bf16 v[24:27], v[80:83], v[228:231], v[24:27]
	v_mfma_f32_16x16x32_bf16 v[8:11], v[80:83], v[236:239], v[8:11]
	v_mfma_f32_16x16x32_bf16 v[12:15], v[72:75], v[236:239], v[12:15]
	v_mfma_f32_16x16x32_bf16 v[60:63], v[76:79], v[214:217], v[60:63]
	v_mfma_f32_16x16x32_bf16 v[56:59], v[88:91], v[214:217], v[56:59]
	v_mfma_f32_16x16x32_bf16 v[40:43], v[88:91], v[224:227], v[40:43]
	v_mfma_f32_16x16x32_bf16 v[44:47], v[76:79], v[224:227], v[44:47]
	v_mfma_f32_16x16x32_bf16 v[28:31], v[76:79], v[232:235], v[28:31]
	v_mfma_f32_16x16x32_bf16 v[24:27], v[88:91], v[232:235], v[24:27]
	v_mfma_f32_16x16x32_bf16 v[8:11], v[88:91], v[240:243], v[8:11]
	v_mfma_f32_16x16x32_bf16 v[12:15], v[76:79], v[240:243], v[12:15]
	s_setprio 0
	s_setprio 1
	v_mfma_f32_16x16x32_bf16 v[52:55], v[174:177], v[210:213], v[52:55]
	v_mfma_f32_16x16x32_bf16 v[48:51], v[190:193], v[210:213], v[48:51]
	v_mfma_f32_16x16x32_bf16 v[32:35], v[190:193], v[218:221], v[32:35]
	v_mfma_f32_16x16x32_bf16 v[36:39], v[174:177], v[218:221], v[36:39]
	v_mfma_f32_16x16x32_bf16 v[20:23], v[174:177], v[228:231], v[20:23]
	v_mfma_f32_16x16x32_bf16 v[16:19], v[190:193], v[228:231], v[16:19]
	v_mfma_f32_16x16x32_bf16 v[0:3], v[190:193], v[236:239], v[0:3]
	v_mfma_f32_16x16x32_bf16 v[4:7], v[174:177], v[236:239], v[4:7]
	v_mfma_f32_16x16x32_bf16 v[52:55], v[178:181], v[214:217], v[52:55]
	v_mfma_f32_16x16x32_bf16 v[48:51], v[194:197], v[214:217], v[48:51]
	v_mfma_f32_16x16x32_bf16 v[32:35], v[194:197], v[224:227], v[32:35]
	v_mfma_f32_16x16x32_bf16 v[36:39], v[178:181], v[224:227], v[36:39]
	v_mfma_f32_16x16x32_bf16 v[20:23], v[178:181], v[232:235], v[20:23]
	v_mfma_f32_16x16x32_bf16 v[16:19], v[194:197], v[232:235], v[16:19]
	v_mfma_f32_16x16x32_bf16 v[0:3], v[194:197], v[240:243], v[0:3]
	v_mfma_f32_16x16x32_bf16 v[4:7], v[178:181], v[240:243], v[4:7]
	s_setprio 0
	s_barrier
	s_add_i32 s83, 0, 0x18000
	s_add_i32 s84, 0, 0x1c000
	v_add_u32_e32 v88, s83, v185
	v_add_u32_e32 v189, s84, v185
	ds_read_b128 v[72:75], v88
	ds_read_b128 v[76:79], v88 offset:1024
	ds_read_b128 v[80:83], v88 offset:2048
	ds_read_b128 v[88:91], v88 offset:3072
	ds_read_b128 v[174:177], v189
	ds_read_b128 v[178:181], v189 offset:1024
	ds_read_b128 v[190:193], v189 offset:2048
	ds_read_b128 v[194:197], v189 offset:3072
	s_add_u32 s62, s62, 0x40000
	s_addc_u32 s63, s63, 0
	s_mov_b32 m0, s67
	v_lshl_add_u64 v[248:249], s[62:63], 0, v[148:149]
	ds_read_b128 v[210:213], v188 offset:32768
	ds_read_b128 v[214:217], v188 offset:33792
	ds_read_b128 v[218:221], v188 offset:34816
	ds_read_b128 v[224:227], v188 offset:35840
	ds_read_b128 v[228:231], v188 offset:36864
	ds_read_b128 v[232:235], v188 offset:37888
	ds_read_b128 v[236:239], v188 offset:38912
	ds_read_b128 v[240:243], v188 offset:39936
	global_load_lds_dwordx4 v[248:249], off
	v_lshl_add_u64 v[248:249], s[62:63], 0, v[146:147]
	s_mov_b32 m0, s68
	s_nop 0
	global_load_lds_dwordx4 v[248:249], off
	s_waitcnt vmcnt(8)
	s_waitcnt lgkmcnt(0)
	s_barrier
	s_setprio 1
	s_waitcnt lgkmcnt(0)
	v_mfma_f32_16x16x32_bf16 v[140:143], v[72:75], v[210:213], v[140:143]
	v_mfma_f32_16x16x32_bf16 v[136:139], v[80:83], v[210:213], v[136:139]
	v_mfma_f32_16x16x32_bf16 v[120:123], v[80:83], v[218:221], v[120:123]
	v_mfma_f32_16x16x32_bf16 v[124:127], v[72:75], v[218:221], v[124:127]
	v_mfma_f32_16x16x32_bf16 v[108:111], v[72:75], v[228:231], v[108:111]
	v_mfma_f32_16x16x32_bf16 v[104:107], v[80:83], v[228:231], v[104:107]
	v_mfma_f32_16x16x32_bf16 v[84:87], v[80:83], v[236:239], v[84:87]
	v_mfma_f32_16x16x32_bf16 v[92:95], v[72:75], v[236:239], v[92:95]
	v_mfma_f32_16x16x32_bf16 v[140:143], v[76:79], v[214:217], v[140:143]
	v_mfma_f32_16x16x32_bf16 v[136:139], v[88:91], v[214:217], v[136:139]
	v_mfma_f32_16x16x32_bf16 v[120:123], v[88:91], v[224:227], v[120:123]
	v_mfma_f32_16x16x32_bf16 v[124:127], v[76:79], v[224:227], v[124:127]
	v_mfma_f32_16x16x32_bf16 v[108:111], v[76:79], v[232:235], v[108:111]
	v_mfma_f32_16x16x32_bf16 v[104:107], v[88:91], v[232:235], v[104:107]
	v_mfma_f32_16x16x32_bf16 v[84:87], v[88:91], v[240:243], v[84:87]
	v_mfma_f32_16x16x32_bf16 v[92:95], v[76:79], v[240:243], v[92:95]
	s_setprio 0
	s_setprio 1
	v_mfma_f32_16x16x32_bf16 v[132:135], v[174:177], v[210:213], v[132:135]
	v_mfma_f32_16x16x32_bf16 v[128:131], v[190:193], v[210:213], v[128:131]
	v_mfma_f32_16x16x32_bf16 v[112:115], v[190:193], v[218:221], v[112:115]
	v_mfma_f32_16x16x32_bf16 v[116:119], v[174:177], v[218:221], v[116:119]
	v_mfma_f32_16x16x32_bf16 v[100:103], v[174:177], v[228:231], v[100:103]
	v_mfma_f32_16x16x32_bf16 v[96:99], v[190:193], v[228:231], v[96:99]
	v_mfma_f32_16x16x32_bf16 v[64:67], v[190:193], v[236:239], v[64:67]
	v_mfma_f32_16x16x32_bf16 v[68:71], v[174:177], v[236:239], v[68:71]
	v_mfma_f32_16x16x32_bf16 v[132:135], v[178:181], v[214:217], v[132:135]
	v_mfma_f32_16x16x32_bf16 v[128:131], v[194:197], v[214:217], v[128:131]
	v_mfma_f32_16x16x32_bf16 v[112:115], v[194:197], v[224:227], v[112:115]
	v_mfma_f32_16x16x32_bf16 v[116:119], v[178:181], v[224:227], v[116:119]
	v_mfma_f32_16x16x32_bf16 v[100:103], v[178:181], v[232:235], v[100:103]
	v_mfma_f32_16x16x32_bf16 v[96:99], v[194:197], v[232:235], v[96:99]
	v_mfma_f32_16x16x32_bf16 v[64:67], v[194:197], v[240:243], v[64:67]
	v_mfma_f32_16x16x32_bf16 v[68:71], v[178:181], v[240:243], v[68:71]
	s_setprio 0
	s_barrier
	s_add_i32 s62, s83, s8
	v_lshl_add_u64 v[182:183], v[182:183], 0, s[22:23]
	s_mov_b32 m0, s62
	ds_read_b128 v[210:213], v188 offset:49152
	ds_read_b128 v[214:217], v188 offset:50176
	ds_read_b128 v[218:221], v188 offset:51200
	ds_read_b128 v[224:227], v188 offset:52224
	ds_read_b128 v[228:231], v188 offset:53248
	ds_read_b128 v[232:235], v188 offset:54272
	ds_read_b128 v[236:239], v188 offset:55296
	ds_read_b128 v[240:243], v188 offset:56320
	global_load_lds_dwordx4 v[182:183], off
	s_add_i32 m0, s62, 0x2000
	s_add_u32 s44, s44, 0x40080
	v_lshl_add_u64 v[182:183], v[198:199], 0, s[22:23]
	s_addc_u32 s45, s45, 0
	s_add_i32 s62, s84, s8
	global_load_lds_dwordx4 v[182:183], off
	v_lshl_add_u64 v[182:183], s[44:45], 0, v[152:153]
	s_mov_b32 m0, s62
	s_nop 0
	global_load_lds_dwordx4 v[182:183], off
	v_lshl_add_u64 v[182:183], s[44:45], 0, v[144:145]
	s_add_i32 m0, s62, 0x2000
	s_nop 0
	global_load_lds_dwordx4 v[182:183], off
	v_lshl_add_u64 v[182:183], v[244:245], 0, s[22:23]
	s_mov_b32 m0, s69
	s_nop 0
	global_load_lds_dwordx4 v[182:183], off
	v_lshl_add_u64 v[182:183], v[246:247], 0, s[22:23]
	s_mov_b32 m0, s74
	s_nop 0
	global_load_lds_dwordx4 v[182:183], off
	s_waitcnt vmcnt(8)
	s_waitcnt lgkmcnt(0)
	s_barrier
	s_setprio 1
	s_waitcnt lgkmcnt(0)
	v_mfma_f32_16x16x32_bf16 v[60:63], v[72:75], v[210:213], v[60:63]
	v_mfma_f32_16x16x32_bf16 v[56:59], v[80:83], v[210:213], v[56:59]
	v_mfma_f32_16x16x32_bf16 v[40:43], v[80:83], v[218:221], v[40:43]
	v_mfma_f32_16x16x32_bf16 v[44:47], v[72:75], v[218:221], v[44:47]
	v_mfma_f32_16x16x32_bf16 v[28:31], v[72:75], v[228:231], v[28:31]
	v_mfma_f32_16x16x32_bf16 v[24:27], v[80:83], v[228:231], v[24:27]
	v_mfma_f32_16x16x32_bf16 v[8:11], v[80:83], v[236:239], v[8:11]
	v_mfma_f32_16x16x32_bf16 v[12:15], v[72:75], v[236:239], v[12:15]
	v_mfma_f32_16x16x32_bf16 v[60:63], v[76:79], v[214:217], v[60:63]
	v_mfma_f32_16x16x32_bf16 v[56:59], v[88:91], v[214:217], v[56:59]
	v_mfma_f32_16x16x32_bf16 v[40:43], v[88:91], v[224:227], v[40:43]
	v_mfma_f32_16x16x32_bf16 v[44:47], v[76:79], v[224:227], v[44:47]
	v_mfma_f32_16x16x32_bf16 v[28:31], v[76:79], v[232:235], v[28:31]
	v_mfma_f32_16x16x32_bf16 v[24:27], v[88:91], v[232:235], v[24:27]
	v_mfma_f32_16x16x32_bf16 v[8:11], v[88:91], v[240:243], v[8:11]
	v_mfma_f32_16x16x32_bf16 v[12:15], v[76:79], v[240:243], v[12:15]
	s_setprio 0
	s_setprio 1
	v_mfma_f32_16x16x32_bf16 v[52:55], v[174:177], v[210:213], v[52:55]
	v_mfma_f32_16x16x32_bf16 v[48:51], v[190:193], v[210:213], v[48:51]
	v_mfma_f32_16x16x32_bf16 v[32:35], v[190:193], v[218:221], v[32:35]
	v_mfma_f32_16x16x32_bf16 v[36:39], v[174:177], v[218:221], v[36:39]
	v_mfma_f32_16x16x32_bf16 v[20:23], v[174:177], v[228:231], v[20:23]
	v_mfma_f32_16x16x32_bf16 v[16:19], v[190:193], v[228:231], v[16:19]
	v_mfma_f32_16x16x32_bf16 v[0:3], v[190:193], v[236:239], v[0:3]
	v_mfma_f32_16x16x32_bf16 v[4:7], v[174:177], v[236:239], v[4:7]
	v_mfma_f32_16x16x32_bf16 v[52:55], v[178:181], v[214:217], v[52:55]
	v_mfma_f32_16x16x32_bf16 v[48:51], v[194:197], v[214:217], v[48:51]
	v_mfma_f32_16x16x32_bf16 v[32:35], v[194:197], v[224:227], v[32:35]
	v_mfma_f32_16x16x32_bf16 v[36:39], v[178:181], v[224:227], v[36:39]
	v_mfma_f32_16x16x32_bf16 v[20:23], v[178:181], v[232:235], v[20:23]
	v_mfma_f32_16x16x32_bf16 v[16:19], v[194:197], v[232:235], v[16:19]
	v_mfma_f32_16x16x32_bf16 v[0:3], v[194:197], v[240:243], v[0:3]
	v_mfma_f32_16x16x32_bf16 v[4:7], v[178:181], v[240:243], v[4:7]
	s_setprio 0
	s_barrier
	s_add_i32 s82, s82, 2
	s_add_u32 s80, s80, 0x100
	s_addc_u32 s81, s81, 0
	s_add_u32 s48, s48, 0x100
	s_addc_u32 s49, s49, 0
	s_cmp_gt_u32 s82, 13
	s_cbranch_scc0 .LBB0_419
	s_and_b64 vcc, exec, s[16:17]
	s_cbranch_vccz .LBB0_422
	s_barrier

.LBB0_705:
	s_add_u32 s44, s60, 0xfffe0080
	s_addc_u32 s45, s61, -1
	s_add_i32 s83, 0, 0x10000
	s_cmp_eq_u32 s82, 4
	s_cselect_b32 s63, s21, s45
	s_cselect_b32 s62, s78, s44
	s_cselect_b32 s45, s19, s81
	s_cselect_b32 s44, s79, s80
	s_add_i32 s86, 0, 0x14000
	v_add_u32_e32 v140, s83, v195
	v_add_u32_e32 v186, s86, v195
	ds_read_b128 v[124:127], v140
	ds_read_b128 v[132:135], v140 offset:1024
	ds_read_b128 v[136:139], v140 offset:2048
	ds_read_b128 v[140:143], v140 offset:3072
	ds_read_b128 v[144:147], v186
	ds_read_b128 v[148:151], v186 offset:1024
	ds_read_b128 v[182:185], v186 offset:2048
	ds_read_b128 v[186:189], v186 offset:3072
	v_lshl_add_u64 v[198:199], s[60:61], 0, v[180:181]
	s_add_i32 m0, s59, 0xc000
	ds_read_b128 v[190:193], v197
	ds_read_b128 v[210:213], v197 offset:1024
	ds_read_b128 v[214:217], v197 offset:2048
	ds_read_b128 v[218:221], v197 offset:3072
	ds_read_b128 v[224:227], v197 offset:4096
	ds_read_b128 v[228:231], v197 offset:5120
	ds_read_b128 v[232:235], v197 offset:6144
	ds_read_b128 v[236:239], v197 offset:7168
	global_load_lds_dwordx4 v[198:199], off
	v_lshl_add_u64 v[198:199], s[60:61], 0, v[178:179]
	s_add_i32 m0, s59, 0xe000
	s_nop 0
	global_load_lds_dwordx4 v[198:199], off
	s_waitcnt vmcnt(8)
	s_waitcnt lgkmcnt(0)
	s_barrier
	s_setprio 1
	s_waitcnt lgkmcnt(0)
	v_mfma_f32_16x16x32_bf16 v[128:131], v[124:127], v[190:193], v[128:131]
	v_mfma_f32_16x16x32_bf16 v[120:123], v[136:139], v[190:193], v[120:123]
	v_mfma_f32_16x16x32_bf16 v[104:107], v[136:139], v[214:217], v[104:107]
	v_mfma_f32_16x16x32_bf16 v[108:111], v[124:127], v[214:217], v[108:111]
	v_mfma_f32_16x16x32_bf16 v[92:95], v[124:127], v[224:227], v[92:95]
	v_mfma_f32_16x16x32_bf16 v[88:91], v[136:139], v[224:227], v[88:91]
	v_mfma_f32_16x16x32_bf16 v[72:75], v[136:139], v[232:235], v[72:75]
	v_mfma_f32_16x16x32_bf16 v[76:79], v[124:127], v[232:235], v[76:79]
	v_mfma_f32_16x16x32_bf16 v[128:131], v[132:135], v[210:213], v[128:131]
	v_mfma_f32_16x16x32_bf16 v[120:123], v[140:143], v[210:213], v[120:123]
	v_mfma_f32_16x16x32_bf16 v[104:107], v[140:143], v[218:221], v[104:107]
	v_mfma_f32_16x16x32_bf16 v[108:111], v[132:135], v[218:221], v[108:111]
	v_mfma_f32_16x16x32_bf16 v[92:95], v[132:135], v[228:231], v[92:95]
	v_mfma_f32_16x16x32_bf16 v[88:91], v[140:143], v[228:231], v[88:91]
	v_mfma_f32_16x16x32_bf16 v[72:75], v[140:143], v[236:239], v[72:75]
	v_mfma_f32_16x16x32_bf16 v[76:79], v[132:135], v[236:239], v[76:79]
	s_setprio 0
	s_setprio 1
	v_mfma_f32_16x16x32_bf16 v[116:119], v[144:147], v[190:193], v[116:119]
	v_mfma_f32_16x16x32_bf16 v[112:115], v[182:185], v[190:193], v[112:115]
	v_mfma_f32_16x16x32_bf16 v[96:99], v[182:185], v[214:217], v[96:99]
	v_mfma_f32_16x16x32_bf16 v[100:103], v[144:147], v[214:217], v[100:103]
	v_mfma_f32_16x16x32_bf16 v[84:87], v[144:147], v[224:227], v[84:87]
	v_mfma_f32_16x16x32_bf16 v[80:83], v[182:185], v[224:227], v[80:83]
	v_mfma_f32_16x16x32_bf16 v[64:67], v[182:185], v[232:235], v[64:67]
	v_mfma_f32_16x16x32_bf16 v[68:71], v[144:147], v[232:235], v[68:71]
	v_mfma_f32_16x16x32_bf16 v[116:119], v[148:151], v[210:213], v[116:119]
	v_mfma_f32_16x16x32_bf16 v[112:115], v[186:189], v[210:213], v[112:115]
	v_mfma_f32_16x16x32_bf16 v[96:99], v[186:189], v[218:221], v[96:99]
	v_mfma_f32_16x16x32_bf16 v[100:103], v[148:151], v[218:221], v[100:103]
	v_mfma_f32_16x16x32_bf16 v[84:87], v[148:151], v[228:231], v[84:87]
	v_mfma_f32_16x16x32_bf16 v[80:83], v[186:189], v[228:231], v[80:83]
	v_mfma_f32_16x16x32_bf16 v[64:67], v[186:189], v[236:239], v[64:67]
	v_mfma_f32_16x16x32_bf16 v[68:71], v[148:151], v[236:239], v[68:71]
	s_setprio 0
	s_barrier
	s_add_i32 s83, s83, s8
	v_lshl_add_u64 v[198:199], s[44:45], 0, v[152:153]
	s_mov_b32 m0, s83
	ds_read_b128 v[190:193], v197 offset:16384
	ds_read_b128 v[210:213], v197 offset:17408
	ds_read_b128 v[214:217], v197 offset:18432
	ds_read_b128 v[218:221], v197 offset:19456
	ds_read_b128 v[224:227], v197 offset:20480
	ds_read_b128 v[228:231], v197 offset:21504
	ds_read_b128 v[232:235], v197 offset:22528
	ds_read_b128 v[236:239], v197 offset:23552
	global_load_lds_dwordx4 v[198:199], off
	s_add_i32 m0, s83, 0x2000
	s_add_u32 s84, s44, 0x20000
	v_lshl_add_u64 v[240:241], s[44:45], 0, v[172:173]
	s_addc_u32 s85, s45, 0
	s_add_i32 s83, s86, s8
	global_load_lds_dwordx4 v[240:241], off
	v_lshl_add_u64 v[242:243], s[84:85], 0, v[152:153]
	s_mov_b32 m0, s83
	v_lshl_add_u64 v[244:245], s[62:63], 0, v[174:175]
	global_load_lds_dwordx4 v[242:243], off
	v_lshl_add_u64 v[242:243], s[84:85], 0, v[172:173]
	s_add_i32 m0, s83, 0x2000
	s_nop 0
	global_load_lds_dwordx4 v[242:243], off
	v_lshl_add_u64 v[242:243], s[62:63], 0, v[176:177]
	s_mov_b32 m0, s59
	s_nop 0
	global_load_lds_dwordx4 v[242:243], off
	s_mov_b32 m0, s66
	s_nop 0
	global_load_lds_dwordx4 v[244:245], off
	s_waitcnt vmcnt(8)
	s_waitcnt lgkmcnt(0)
	s_barrier
	s_setprio 1
	s_waitcnt lgkmcnt(0)
	v_mfma_f32_16x16x32_bf16 v[60:63], v[124:127], v[190:193], v[60:63]
	v_mfma_f32_16x16x32_bf16 v[56:59], v[136:139], v[190:193], v[56:59]
	v_mfma_f32_16x16x32_bf16 v[40:43], v[136:139], v[214:217], v[40:43]
	v_mfma_f32_16x16x32_bf16 v[48:51], v[124:127], v[214:217], v[48:51]
	v_mfma_f32_16x16x32_bf16 v[32:35], v[124:127], v[224:227], v[32:35]
	v_mfma_f32_16x16x32_bf16 v[24:27], v[136:139], v[224:227], v[24:27]
	v_mfma_f32_16x16x32_bf16 v[8:11], v[136:139], v[232:235], v[8:11]
	v_mfma_f32_16x16x32_bf16 v[16:19], v[124:127], v[232:235], v[16:19]
	v_mfma_f32_16x16x32_bf16 v[60:63], v[132:135], v[210:213], v[60:63]
	v_mfma_f32_16x16x32_bf16 v[56:59], v[140:143], v[210:213], v[56:59]
	v_mfma_f32_16x16x32_bf16 v[40:43], v[140:143], v[218:221], v[40:43]
	v_mfma_f32_16x16x32_bf16 v[48:51], v[132:135], v[218:221], v[48:51]
	v_mfma_f32_16x16x32_bf16 v[32:35], v[132:135], v[228:231], v[32:35]
	v_mfma_f32_16x16x32_bf16 v[24:27], v[140:143], v[228:231], v[24:27]
	v_mfma_f32_16x16x32_bf16 v[8:11], v[140:143], v[236:239], v[8:11]
	v_mfma_f32_16x16x32_bf16 v[16:19], v[132:135], v[236:239], v[16:19]
	s_setprio 0
	s_setprio 1
	v_mfma_f32_16x16x32_bf16 v[52:55], v[144:147], v[190:193], v[52:55]
	v_mfma_f32_16x16x32_bf16 v[44:47], v[182:185], v[190:193], v[44:47]
	v_mfma_f32_16x16x32_bf16 v[28:31], v[182:185], v[214:217], v[28:31]
	v_mfma_f32_16x16x32_bf16 v[36:39], v[144:147], v[214:217], v[36:39]
	v_mfma_f32_16x16x32_bf16 v[20:23], v[144:147], v[224:227], v[20:23]
	v_mfma_f32_16x16x32_bf16 v[12:15], v[182:185], v[224:227], v[12:15]
	v_mfma_f32_16x16x32_bf16 v[0:3], v[182:185], v[232:235], v[0:3]
	v_mfma_f32_16x16x32_bf16 v[4:7], v[144:147], v[232:235], v[4:7]
	v_mfma_f32_16x16x32_bf16 v[52:55], v[148:151], v[210:213], v[52:55]
	v_mfma_f32_16x16x32_bf16 v[44:47], v[186:189], v[210:213], v[44:47]
	v_mfma_f32_16x16x32_bf16 v[28:31], v[186:189], v[218:221], v[28:31]
	v_mfma_f32_16x16x32_bf16 v[36:39], v[148:151], v[218:221], v[36:39]
	v_mfma_f32_16x16x32_bf16 v[20:23], v[148:151], v[228:231], v[20:23]
	v_mfma_f32_16x16x32_bf16 v[12:15], v[186:189], v[228:231], v[12:15]
	v_mfma_f32_16x16x32_bf16 v[0:3], v[186:189], v[236:239], v[0:3]
	v_mfma_f32_16x16x32_bf16 v[4:7], v[148:151], v[236:239], v[4:7]
	s_setprio 0
	s_barrier
	s_add_i32 s83, 0, 0x18000
	s_add_i32 s84, 0, 0x1c000
	v_add_u32_e32 v140, s83, v195
	v_add_u32_e32 v186, s84, v195
	ds_read_b128 v[124:127], v140
	ds_read_b128 v[132:135], v140 offset:1024
	ds_read_b128 v[136:139], v140 offset:2048
	ds_read_b128 v[140:143], v140 offset:3072
	ds_read_b128 v[144:147], v186
	ds_read_b128 v[148:151], v186 offset:1024
	ds_read_b128 v[182:185], v186 offset:2048
	ds_read_b128 v[186:189], v186 offset:3072
	s_add_u32 s62, s62, 0x20000
	s_addc_u32 s63, s63, 0
	s_mov_b32 m0, s67
	v_lshl_add_u64 v[246:247], s[62:63], 0, v[176:177]
	ds_read_b128 v[190:193], v197 offset:32768
	ds_read_b128 v[210:213], v197 offset:33792
	ds_read_b128 v[214:217], v197 offset:34816
	ds_read_b128 v[218:221], v197 offset:35840
	ds_read_b128 v[224:227], v197 offset:36864
	ds_read_b128 v[228:231], v197 offset:37888
	ds_read_b128 v[232:235], v197 offset:38912
	ds_read_b128 v[236:239], v197 offset:39936
	global_load_lds_dwordx4 v[246:247], off
	v_lshl_add_u64 v[246:247], s[62:63], 0, v[174:175]
	s_mov_b32 m0, s68
	s_nop 0
	global_load_lds_dwordx4 v[246:247], off
	s_waitcnt vmcnt(8)
	s_waitcnt lgkmcnt(0)
	s_barrier
	s_setprio 1
	s_waitcnt lgkmcnt(0)
	v_mfma_f32_16x16x32_bf16 v[128:131], v[124:127], v[190:193], v[128:131]
	v_mfma_f32_16x16x32_bf16 v[120:123], v[136:139], v[190:193], v[120:123]
	v_mfma_f32_16x16x32_bf16 v[104:107], v[136:139], v[214:217], v[104:107]
	v_mfma_f32_16x16x32_bf16 v[108:111], v[124:127], v[214:217], v[108:111]
	v_mfma_f32_16x16x32_bf16 v[92:95], v[124:127], v[224:227], v[92:95]
	v_mfma_f32_16x16x32_bf16 v[88:91], v[136:139], v[224:227], v[88:91]
	v_mfma_f32_16x16x32_bf16 v[72:75], v[136:139], v[232:235], v[72:75]
	v_mfma_f32_16x16x32_bf16 v[76:79], v[124:127], v[232:235], v[76:79]
	v_mfma_f32_16x16x32_bf16 v[128:131], v[132:135], v[210:213], v[128:131]
	v_mfma_f32_16x16x32_bf16 v[120:123], v[140:143], v[210:213], v[120:123]
	v_mfma_f32_16x16x32_bf16 v[104:107], v[140:143], v[218:221], v[104:107]
	v_mfma_f32_16x16x32_bf16 v[108:111], v[132:135], v[218:221], v[108:111]
	v_mfma_f32_16x16x32_bf16 v[92:95], v[132:135], v[228:231], v[92:95]
	v_mfma_f32_16x16x32_bf16 v[88:91], v[140:143], v[228:231], v[88:91]
	v_mfma_f32_16x16x32_bf16 v[72:75], v[140:143], v[236:239], v[72:75]
	v_mfma_f32_16x16x32_bf16 v[76:79], v[132:135], v[236:239], v[76:79]
	s_setprio 0
	s_setprio 1
	v_mfma_f32_16x16x32_bf16 v[116:119], v[144:147], v[190:193], v[116:119]
	v_mfma_f32_16x16x32_bf16 v[112:115], v[182:185], v[190:193], v[112:115]
	v_mfma_f32_16x16x32_bf16 v[96:99], v[182:185], v[214:217], v[96:99]
	v_mfma_f32_16x16x32_bf16 v[100:103], v[144:147], v[214:217], v[100:103]
	v_mfma_f32_16x16x32_bf16 v[84:87], v[144:147], v[224:227], v[84:87]
	v_mfma_f32_16x16x32_bf16 v[80:83], v[182:185], v[224:227], v[80:83]
	v_mfma_f32_16x16x32_bf16 v[64:67], v[182:185], v[232:235], v[64:67]
	v_mfma_f32_16x16x32_bf16 v[68:71], v[144:147], v[232:235], v[68:71]
	v_mfma_f32_16x16x32_bf16 v[116:119], v[148:151], v[210:213], v[116:119]
	v_mfma_f32_16x16x32_bf16 v[112:115], v[186:189], v[210:213], v[112:115]
	v_mfma_f32_16x16x32_bf16 v[96:99], v[186:189], v[218:221], v[96:99]
	v_mfma_f32_16x16x32_bf16 v[100:103], v[148:151], v[218:221], v[100:103]
	v_mfma_f32_16x16x32_bf16 v[84:87], v[148:151], v[228:231], v[84:87]
	v_mfma_f32_16x16x32_bf16 v[80:83], v[186:189], v[228:231], v[80:83]
	v_mfma_f32_16x16x32_bf16 v[64:67], v[186:189], v[236:239], v[64:67]
	v_mfma_f32_16x16x32_bf16 v[68:71], v[148:151], v[236:239], v[68:71]
	s_setprio 0
	s_barrier
	s_add_i32 s62, s83, s8
	v_lshl_add_u64 v[198:199], v[198:199], 0, s[22:23]
	s_mov_b32 m0, s62
	ds_read_b128 v[190:193], v197 offset:49152
	ds_read_b128 v[210:213], v197 offset:50176
	ds_read_b128 v[214:217], v197 offset:51200
	ds_read_b128 v[218:221], v197 offset:52224
	ds_read_b128 v[224:227], v197 offset:53248
	ds_read_b128 v[228:231], v197 offset:54272
	ds_read_b128 v[232:235], v197 offset:55296
	ds_read_b128 v[236:239], v197 offset:56320
	global_load_lds_dwordx4 v[198:199], off
	s_add_i32 m0, s62, 0x2000
	s_add_u32 s44, s44, 0x20080
	v_lshl_add_u64 v[198:199], v[240:241], 0, s[22:23]
	s_addc_u32 s45, s45, 0
	s_add_i32 s62, s84, s8
	global_load_lds_dwordx4 v[198:199], off
	v_lshl_add_u64 v[198:199], s[44:45], 0, v[152:153]
	s_mov_b32 m0, s62
	s_nop 0
	global_load_lds_dwordx4 v[198:199], off
	v_lshl_add_u64 v[198:199], s[44:45], 0, v[172:173]
	s_add_i32 m0, s62, 0x2000
	s_nop 0
	global_load_lds_dwordx4 v[198:199], off
	v_lshl_add_u64 v[198:199], v[242:243], 0, s[22:23]
	s_mov_b32 m0, s69
	s_nop 0
	global_load_lds_dwordx4 v[198:199], off
	v_lshl_add_u64 v[198:199], v[244:245], 0, s[22:23]
	s_mov_b32 m0, s74
	s_nop 0
	global_load_lds_dwordx4 v[198:199], off
	s_waitcnt vmcnt(8)
	s_waitcnt lgkmcnt(0)
	s_barrier
	s_setprio 1
	s_waitcnt lgkmcnt(0)
	v_mfma_f32_16x16x32_bf16 v[60:63], v[124:127], v[190:193], v[60:63]
	v_mfma_f32_16x16x32_bf16 v[56:59], v[136:139], v[190:193], v[56:59]
	v_mfma_f32_16x16x32_bf16 v[40:43], v[136:139], v[214:217], v[40:43]
	v_mfma_f32_16x16x32_bf16 v[48:51], v[124:127], v[214:217], v[48:51]
	v_mfma_f32_16x16x32_bf16 v[32:35], v[124:127], v[224:227], v[32:35]
	v_mfma_f32_16x16x32_bf16 v[24:27], v[136:139], v[224:227], v[24:27]
	v_mfma_f32_16x16x32_bf16 v[8:11], v[136:139], v[232:235], v[8:11]
	v_mfma_f32_16x16x32_bf16 v[16:19], v[124:127], v[232:235], v[16:19]
	v_mfma_f32_16x16x32_bf16 v[60:63], v[132:135], v[210:213], v[60:63]
	v_mfma_f32_16x16x32_bf16 v[56:59], v[140:143], v[210:213], v[56:59]
	v_mfma_f32_16x16x32_bf16 v[40:43], v[140:143], v[218:221], v[40:43]
	v_mfma_f32_16x16x32_bf16 v[48:51], v[132:135], v[218:221], v[48:51]
	v_mfma_f32_16x16x32_bf16 v[32:35], v[132:135], v[228:231], v[32:35]
	v_mfma_f32_16x16x32_bf16 v[24:27], v[140:143], v[228:231], v[24:27]
	v_mfma_f32_16x16x32_bf16 v[8:11], v[140:143], v[236:239], v[8:11]
	v_mfma_f32_16x16x32_bf16 v[16:19], v[132:135], v[236:239], v[16:19]
	s_setprio 0
	s_setprio 1
	v_mfma_f32_16x16x32_bf16 v[52:55], v[144:147], v[190:193], v[52:55]
	v_mfma_f32_16x16x32_bf16 v[44:47], v[182:185], v[190:193], v[44:47]
	v_mfma_f32_16x16x32_bf16 v[28:31], v[182:185], v[214:217], v[28:31]
	v_mfma_f32_16x16x32_bf16 v[36:39], v[144:147], v[214:217], v[36:39]
	v_mfma_f32_16x16x32_bf16 v[20:23], v[144:147], v[224:227], v[20:23]
	v_mfma_f32_16x16x32_bf16 v[12:15], v[182:185], v[224:227], v[12:15]
	v_mfma_f32_16x16x32_bf16 v[0:3], v[182:185], v[232:235], v[0:3]
	v_mfma_f32_16x16x32_bf16 v[4:7], v[144:147], v[232:235], v[4:7]
	v_mfma_f32_16x16x32_bf16 v[52:55], v[148:151], v[210:213], v[52:55]
	v_mfma_f32_16x16x32_bf16 v[44:47], v[186:189], v[210:213], v[44:47]
	v_mfma_f32_16x16x32_bf16 v[28:31], v[186:189], v[218:221], v[28:31]
	v_mfma_f32_16x16x32_bf16 v[36:39], v[148:151], v[218:221], v[36:39]
	v_mfma_f32_16x16x32_bf16 v[20:23], v[148:151], v[228:231], v[20:23]
	v_mfma_f32_16x16x32_bf16 v[12:15], v[186:189], v[228:231], v[12:15]
	v_mfma_f32_16x16x32_bf16 v[0:3], v[186:189], v[236:239], v[0:3]
	v_mfma_f32_16x16x32_bf16 v[4:7], v[148:151], v[236:239], v[4:7]
	s_setprio 0
	s_barrier
	s_add_i32 s82, s82, 2
	s_add_u32 s80, s80, 0x100
	s_addc_u32 s81, s81, 0
	s_add_u32 s60, s60, 0x100
	s_addc_u32 s61, s61, 0
	s_cmp_gt_u32 s82, 5
	s_cbranch_scc0 .LBB0_705
	s_and_b64 vcc, exec, s[16:17]
	s_cbranch_vccz .LBB0_708
	s_barrier

.LBB0_725:
	s_add_u32 s44, s60, 0xfffe0080
	s_addc_u32 s45, s61, -1
	s_add_i32 s83, 0, 0x10000
	s_cmp_eq_u32 s82, 4
	s_cselect_b32 s63, s21, s45
	s_cselect_b32 s62, s78, s44
	s_cselect_b32 s45, s19, s81
	s_cselect_b32 s44, s79, s80
	s_add_i32 s86, 0, 0x14000
	v_add_u32_e32 v140, s83, v181
	v_add_u32_e32 v178, s86, v181
	ds_read_b128 v[128:131], v140
	ds_read_b128 v[132:135], v140 offset:1024
	ds_read_b128 v[136:139], v140 offset:2048
	ds_read_b128 v[140:143], v140 offset:3072
	ds_read_b128 v[174:177], v178
	ds_read_b128 v[184:187], v178 offset:1024
	ds_read_b128 v[188:191], v178 offset:2048
	ds_read_b128 v[192:195], v178 offset:3072
	v_lshl_add_u64 v[178:179], s[60:61], 0, v[172:173]
	s_add_i32 m0, s59, 0xc000
	ds_read_b128 v[196:199], v183
	ds_read_b128 v[210:213], v183 offset:1024
	ds_read_b128 v[214:217], v183 offset:2048
	ds_read_b128 v[218:221], v183 offset:3072
	ds_read_b128 v[224:227], v183 offset:4096
	ds_read_b128 v[228:231], v183 offset:5120
	ds_read_b128 v[232:235], v183 offset:6144
	ds_read_b128 v[236:239], v183 offset:7168
	global_load_lds_dwordx4 v[178:179], off
	v_lshl_add_u64 v[178:179], s[60:61], 0, v[150:151]
	s_add_i32 m0, s59, 0xe000
	s_nop 0
	global_load_lds_dwordx4 v[178:179], off
	s_waitcnt vmcnt(8)
	s_waitcnt lgkmcnt(0)
	s_barrier
	s_setprio 1
	s_waitcnt lgkmcnt(0)
	v_mfma_f32_16x16x32_bf16 v[124:127], v[128:131], v[196:199], v[124:127]
	v_mfma_f32_16x16x32_bf16 v[120:123], v[136:139], v[196:199], v[120:123]
	v_mfma_f32_16x16x32_bf16 v[104:107], v[136:139], v[214:217], v[104:107]
	v_mfma_f32_16x16x32_bf16 v[108:111], v[128:131], v[214:217], v[108:111]
	v_mfma_f32_16x16x32_bf16 v[92:95], v[128:131], v[224:227], v[92:95]
	v_mfma_f32_16x16x32_bf16 v[88:91], v[136:139], v[224:227], v[88:91]
	v_mfma_f32_16x16x32_bf16 v[72:75], v[136:139], v[232:235], v[72:75]
	v_mfma_f32_16x16x32_bf16 v[76:79], v[128:131], v[232:235], v[76:79]
	v_mfma_f32_16x16x32_bf16 v[124:127], v[132:135], v[210:213], v[124:127]
	v_mfma_f32_16x16x32_bf16 v[120:123], v[140:143], v[210:213], v[120:123]
	v_mfma_f32_16x16x32_bf16 v[104:107], v[140:143], v[218:221], v[104:107]
	v_mfma_f32_16x16x32_bf16 v[108:111], v[132:135], v[218:221], v[108:111]
	v_mfma_f32_16x16x32_bf16 v[92:95], v[132:135], v[228:231], v[92:95]
	v_mfma_f32_16x16x32_bf16 v[88:91], v[140:143], v[228:231], v[88:91]
	v_mfma_f32_16x16x32_bf16 v[72:75], v[140:143], v[236:239], v[72:75]
	v_mfma_f32_16x16x32_bf16 v[76:79], v[132:135], v[236:239], v[76:79]
	s_setprio 0
	s_setprio 1
	v_mfma_f32_16x16x32_bf16 v[116:119], v[174:177], v[196:199], v[116:119]
	v_mfma_f32_16x16x32_bf16 v[112:115], v[188:191], v[196:199], v[112:115]
	v_mfma_f32_16x16x32_bf16 v[96:99], v[188:191], v[214:217], v[96:99]
	v_mfma_f32_16x16x32_bf16 v[100:103], v[174:177], v[214:217], v[100:103]
	v_mfma_f32_16x16x32_bf16 v[84:87], v[174:177], v[224:227], v[84:87]
	v_mfma_f32_16x16x32_bf16 v[80:83], v[188:191], v[224:227], v[80:83]
	v_mfma_f32_16x16x32_bf16 v[64:67], v[188:191], v[232:235], v[64:67]
	v_mfma_f32_16x16x32_bf16 v[68:71], v[174:177], v[232:235], v[68:71]
	v_mfma_f32_16x16x32_bf16 v[116:119], v[184:187], v[210:213], v[116:119]
	v_mfma_f32_16x16x32_bf16 v[112:115], v[192:195], v[210:213], v[112:115]
	v_mfma_f32_16x16x32_bf16 v[96:99], v[192:195], v[218:221], v[96:99]
	v_mfma_f32_16x16x32_bf16 v[100:103], v[184:187], v[218:221], v[100:103]
	v_mfma_f32_16x16x32_bf16 v[84:87], v[184:187], v[228:231], v[84:87]
	v_mfma_f32_16x16x32_bf16 v[80:83], v[192:195], v[228:231], v[80:83]
	v_mfma_f32_16x16x32_bf16 v[64:67], v[192:195], v[236:239], v[64:67]
	v_mfma_f32_16x16x32_bf16 v[68:71], v[184:187], v[236:239], v[68:71]
	s_setprio 0
	s_barrier
	s_add_i32 s83, s83, s8
	v_lshl_add_u64 v[178:179], s[44:45], 0, v[152:153]
	s_mov_b32 m0, s83
	ds_read_b128 v[196:199], v183 offset:16384
	ds_read_b128 v[210:213], v183 offset:17408
	ds_read_b128 v[214:217], v183 offset:18432
	ds_read_b128 v[218:221], v183 offset:19456
	ds_read_b128 v[224:227], v183 offset:20480
	ds_read_b128 v[228:231], v183 offset:21504
	ds_read_b128 v[232:235], v183 offset:22528
	ds_read_b128 v[236:239], v183 offset:23552
	global_load_lds_dwordx4 v[178:179], off
	s_add_i32 m0, s83, 0x2000
	s_add_u32 s84, s44, 0x20000
	v_lshl_add_u64 v[240:241], s[44:45], 0, v[144:145]
	s_addc_u32 s85, s45, 0
	s_add_i32 s83, s86, s8
	global_load_lds_dwordx4 v[240:241], off
	v_lshl_add_u64 v[242:243], s[84:85], 0, v[152:153]
	s_mov_b32 m0, s83
	v_lshl_add_u64 v[244:245], s[62:63], 0, v[146:147]
	global_load_lds_dwordx4 v[242:243], off
	v_lshl_add_u64 v[242:243], s[84:85], 0, v[144:145]
	s_add_i32 m0, s83, 0x2000
	s_nop 0
	global_load_lds_dwordx4 v[242:243], off
	v_lshl_add_u64 v[242:243], s[62:63], 0, v[148:149]
	s_mov_b32 m0, s59
	s_nop 0
	global_load_lds_dwordx4 v[242:243], off
	s_mov_b32 m0, s66
	s_nop 0
	global_load_lds_dwordx4 v[244:245], off
	s_waitcnt vmcnt(8)
	s_waitcnt lgkmcnt(0)
	s_barrier
	s_setprio 1
	s_waitcnt lgkmcnt(0)
	v_mfma_f32_16x16x32_bf16 v[60:63], v[128:131], v[196:199], v[60:63]
	v_mfma_f32_16x16x32_bf16 v[56:59], v[136:139], v[196:199], v[56:59]
	v_mfma_f32_16x16x32_bf16 v[40:43], v[136:139], v[214:217], v[40:43]
	v_mfma_f32_16x16x32_bf16 v[44:47], v[128:131], v[214:217], v[44:47]
	v_mfma_f32_16x16x32_bf16 v[28:31], v[128:131], v[224:227], v[28:31]
	v_mfma_f32_16x16x32_bf16 v[24:27], v[136:139], v[224:227], v[24:27]
	v_mfma_f32_16x16x32_bf16 v[8:11], v[136:139], v[232:235], v[8:11]
	v_mfma_f32_16x16x32_bf16 v[12:15], v[128:131], v[232:235], v[12:15]
	v_mfma_f32_16x16x32_bf16 v[60:63], v[132:135], v[210:213], v[60:63]
	v_mfma_f32_16x16x32_bf16 v[56:59], v[140:143], v[210:213], v[56:59]
	v_mfma_f32_16x16x32_bf16 v[40:43], v[140:143], v[218:221], v[40:43]
	v_mfma_f32_16x16x32_bf16 v[44:47], v[132:135], v[218:221], v[44:47]
	v_mfma_f32_16x16x32_bf16 v[28:31], v[132:135], v[228:231], v[28:31]
	v_mfma_f32_16x16x32_bf16 v[24:27], v[140:143], v[228:231], v[24:27]
	v_mfma_f32_16x16x32_bf16 v[8:11], v[140:143], v[236:239], v[8:11]
	v_mfma_f32_16x16x32_bf16 v[12:15], v[132:135], v[236:239], v[12:15]
	s_setprio 0
	s_setprio 1
	v_mfma_f32_16x16x32_bf16 v[52:55], v[174:177], v[196:199], v[52:55]
	v_mfma_f32_16x16x32_bf16 v[48:51], v[188:191], v[196:199], v[48:51]
	v_mfma_f32_16x16x32_bf16 v[32:35], v[188:191], v[214:217], v[32:35]
	v_mfma_f32_16x16x32_bf16 v[36:39], v[174:177], v[214:217], v[36:39]
	v_mfma_f32_16x16x32_bf16 v[20:23], v[174:177], v[224:227], v[20:23]
	v_mfma_f32_16x16x32_bf16 v[16:19], v[188:191], v[224:227], v[16:19]
	v_mfma_f32_16x16x32_bf16 v[0:3], v[188:191], v[232:235], v[0:3]
	v_mfma_f32_16x16x32_bf16 v[4:7], v[174:177], v[232:235], v[4:7]
	v_mfma_f32_16x16x32_bf16 v[52:55], v[184:187], v[210:213], v[52:55]
	v_mfma_f32_16x16x32_bf16 v[48:51], v[192:195], v[210:213], v[48:51]
	v_mfma_f32_16x16x32_bf16 v[32:35], v[192:195], v[218:221], v[32:35]
	v_mfma_f32_16x16x32_bf16 v[36:39], v[184:187], v[218:221], v[36:39]
	v_mfma_f32_16x16x32_bf16 v[20:23], v[184:187], v[228:231], v[20:23]
	v_mfma_f32_16x16x32_bf16 v[16:19], v[192:195], v[228:231], v[16:19]
	v_mfma_f32_16x16x32_bf16 v[0:3], v[192:195], v[236:239], v[0:3]
	v_mfma_f32_16x16x32_bf16 v[4:7], v[184:187], v[236:239], v[4:7]
	s_setprio 0
	s_barrier
	s_add_i32 s83, 0, 0x18000
	s_add_i32 s84, 0, 0x1c000
	v_add_u32_e32 v140, s83, v181
	v_add_u32_e32 v192, s84, v181
	ds_read_b128 v[128:131], v140
	ds_read_b128 v[132:135], v140 offset:1024
	ds_read_b128 v[136:139], v140 offset:2048
	ds_read_b128 v[140:143], v140 offset:3072
	ds_read_b128 v[174:177], v192
	ds_read_b128 v[184:187], v192 offset:1024
	ds_read_b128 v[188:191], v192 offset:2048
	ds_read_b128 v[192:195], v192 offset:3072
	s_add_u32 s62, s62, 0x20000
	s_addc_u32 s63, s63, 0
	s_mov_b32 m0, s67
	v_lshl_add_u64 v[246:247], s[62:63], 0, v[148:149]
	ds_read_b128 v[196:199], v183 offset:32768
	ds_read_b128 v[210:213], v183 offset:33792
	ds_read_b128 v[214:217], v183 offset:34816
	ds_read_b128 v[218:221], v183 offset:35840
	ds_read_b128 v[224:227], v183 offset:36864
	ds_read_b128 v[228:231], v183 offset:37888
	ds_read_b128 v[232:235], v183 offset:38912
	ds_read_b128 v[236:239], v183 offset:39936
	global_load_lds_dwordx4 v[246:247], off
	v_lshl_add_u64 v[246:247], s[62:63], 0, v[146:147]
	s_mov_b32 m0, s68
	s_nop 0
	global_load_lds_dwordx4 v[246:247], off
	s_waitcnt vmcnt(8)
	s_waitcnt lgkmcnt(0)
	s_barrier
	s_setprio 1
	s_waitcnt lgkmcnt(0)
	v_mfma_f32_16x16x32_bf16 v[124:127], v[128:131], v[196:199], v[124:127]
	v_mfma_f32_16x16x32_bf16 v[120:123], v[136:139], v[196:199], v[120:123]
	v_mfma_f32_16x16x32_bf16 v[104:107], v[136:139], v[214:217], v[104:107]
	v_mfma_f32_16x16x32_bf16 v[108:111], v[128:131], v[214:217], v[108:111]
	v_mfma_f32_16x16x32_bf16 v[92:95], v[128:131], v[224:227], v[92:95]
	v_mfma_f32_16x16x32_bf16 v[88:91], v[136:139], v[224:227], v[88:91]
	v_mfma_f32_16x16x32_bf16 v[72:75], v[136:139], v[232:235], v[72:75]
	v_mfma_f32_16x16x32_bf16 v[76:79], v[128:131], v[232:235], v[76:79]
	v_mfma_f32_16x16x32_bf16 v[124:127], v[132:135], v[210:213], v[124:127]
	v_mfma_f32_16x16x32_bf16 v[120:123], v[140:143], v[210:213], v[120:123]
	v_mfma_f32_16x16x32_bf16 v[104:107], v[140:143], v[218:221], v[104:107]
	v_mfma_f32_16x16x32_bf16 v[108:111], v[132:135], v[218:221], v[108:111]
	v_mfma_f32_16x16x32_bf16 v[92:95], v[132:135], v[228:231], v[92:95]
	v_mfma_f32_16x16x32_bf16 v[88:91], v[140:143], v[228:231], v[88:91]
	v_mfma_f32_16x16x32_bf16 v[72:75], v[140:143], v[236:239], v[72:75]
	v_mfma_f32_16x16x32_bf16 v[76:79], v[132:135], v[236:239], v[76:79]
	s_setprio 0
	s_setprio 1
	v_mfma_f32_16x16x32_bf16 v[116:119], v[174:177], v[196:199], v[116:119]
	v_mfma_f32_16x16x32_bf16 v[112:115], v[188:191], v[196:199], v[112:115]
	v_mfma_f32_16x16x32_bf16 v[96:99], v[188:191], v[214:217], v[96:99]
	v_mfma_f32_16x16x32_bf16 v[100:103], v[174:177], v[214:217], v[100:103]
	v_mfma_f32_16x16x32_bf16 v[84:87], v[174:177], v[224:227], v[84:87]
	v_mfma_f32_16x16x32_bf16 v[80:83], v[188:191], v[224:227], v[80:83]
	v_mfma_f32_16x16x32_bf16 v[64:67], v[188:191], v[232:235], v[64:67]
	v_mfma_f32_16x16x32_bf16 v[68:71], v[174:177], v[232:235], v[68:71]
	v_mfma_f32_16x16x32_bf16 v[116:119], v[184:187], v[210:213], v[116:119]
	v_mfma_f32_16x16x32_bf16 v[112:115], v[192:195], v[210:213], v[112:115]
	v_mfma_f32_16x16x32_bf16 v[96:99], v[192:195], v[218:221], v[96:99]
	v_mfma_f32_16x16x32_bf16 v[100:103], v[184:187], v[218:221], v[100:103]
	v_mfma_f32_16x16x32_bf16 v[84:87], v[184:187], v[228:231], v[84:87]
	v_mfma_f32_16x16x32_bf16 v[80:83], v[192:195], v[228:231], v[80:83]
	v_mfma_f32_16x16x32_bf16 v[64:67], v[192:195], v[236:239], v[64:67]
	v_mfma_f32_16x16x32_bf16 v[68:71], v[184:187], v[236:239], v[68:71]
	s_setprio 0
	s_barrier
	s_add_i32 s62, s83, s8
	v_lshl_add_u64 v[178:179], v[178:179], 0, s[22:23]
	s_mov_b32 m0, s62
	ds_read_b128 v[196:199], v183 offset:49152
	ds_read_b128 v[210:213], v183 offset:50176
	ds_read_b128 v[214:217], v183 offset:51200
	ds_read_b128 v[218:221], v183 offset:52224
	ds_read_b128 v[224:227], v183 offset:53248
	ds_read_b128 v[228:231], v183 offset:54272
	ds_read_b128 v[232:235], v183 offset:55296
	ds_read_b128 v[236:239], v183 offset:56320
	global_load_lds_dwordx4 v[178:179], off
	s_add_i32 m0, s62, 0x2000
	s_add_u32 s44, s44, 0x20080
	v_lshl_add_u64 v[178:179], v[240:241], 0, s[22:23]
	s_addc_u32 s45, s45, 0
	s_add_i32 s62, s84, s8
	global_load_lds_dwordx4 v[178:179], off
	v_lshl_add_u64 v[178:179], s[44:45], 0, v[152:153]
	s_mov_b32 m0, s62
	s_nop 0
	global_load_lds_dwordx4 v[178:179], off
	v_lshl_add_u64 v[178:179], s[44:45], 0, v[144:145]
	s_add_i32 m0, s62, 0x2000
	s_nop 0
	global_load_lds_dwordx4 v[178:179], off
	v_lshl_add_u64 v[178:179], v[242:243], 0, s[22:23]
	s_mov_b32 m0, s69
	s_nop 0
	global_load_lds_dwordx4 v[178:179], off
	v_lshl_add_u64 v[178:179], v[244:245], 0, s[22:23]
	s_mov_b32 m0, s74
	s_nop 0
	global_load_lds_dwordx4 v[178:179], off
	s_waitcnt vmcnt(8)
	s_waitcnt lgkmcnt(0)
	s_barrier
	s_setprio 1
	s_waitcnt lgkmcnt(0)
	v_mfma_f32_16x16x32_bf16 v[60:63], v[128:131], v[196:199], v[60:63]
	v_mfma_f32_16x16x32_bf16 v[56:59], v[136:139], v[196:199], v[56:59]
	v_mfma_f32_16x16x32_bf16 v[40:43], v[136:139], v[214:217], v[40:43]
	v_mfma_f32_16x16x32_bf16 v[44:47], v[128:131], v[214:217], v[44:47]
	v_mfma_f32_16x16x32_bf16 v[28:31], v[128:131], v[224:227], v[28:31]
	v_mfma_f32_16x16x32_bf16 v[24:27], v[136:139], v[224:227], v[24:27]
	v_mfma_f32_16x16x32_bf16 v[8:11], v[136:139], v[232:235], v[8:11]
	v_mfma_f32_16x16x32_bf16 v[12:15], v[128:131], v[232:235], v[12:15]
	v_mfma_f32_16x16x32_bf16 v[60:63], v[132:135], v[210:213], v[60:63]
	v_mfma_f32_16x16x32_bf16 v[56:59], v[140:143], v[210:213], v[56:59]
	v_mfma_f32_16x16x32_bf16 v[40:43], v[140:143], v[218:221], v[40:43]
	v_mfma_f32_16x16x32_bf16 v[44:47], v[132:135], v[218:221], v[44:47]
	v_mfma_f32_16x16x32_bf16 v[28:31], v[132:135], v[228:231], v[28:31]
	v_mfma_f32_16x16x32_bf16 v[24:27], v[140:143], v[228:231], v[24:27]
	v_mfma_f32_16x16x32_bf16 v[8:11], v[140:143], v[236:239], v[8:11]
	v_mfma_f32_16x16x32_bf16 v[12:15], v[132:135], v[236:239], v[12:15]
	s_setprio 0
	s_setprio 1
	v_mfma_f32_16x16x32_bf16 v[52:55], v[174:177], v[196:199], v[52:55]
	v_mfma_f32_16x16x32_bf16 v[48:51], v[188:191], v[196:199], v[48:51]
	v_mfma_f32_16x16x32_bf16 v[32:35], v[188:191], v[214:217], v[32:35]
	v_mfma_f32_16x16x32_bf16 v[36:39], v[174:177], v[214:217], v[36:39]
	v_mfma_f32_16x16x32_bf16 v[20:23], v[174:177], v[224:227], v[20:23]
	v_mfma_f32_16x16x32_bf16 v[16:19], v[188:191], v[224:227], v[16:19]
	v_mfma_f32_16x16x32_bf16 v[0:3], v[188:191], v[232:235], v[0:3]
	v_mfma_f32_16x16x32_bf16 v[4:7], v[174:177], v[232:235], v[4:7]
	v_mfma_f32_16x16x32_bf16 v[52:55], v[184:187], v[210:213], v[52:55]
	v_mfma_f32_16x16x32_bf16 v[48:51], v[192:195], v[210:213], v[48:51]
	v_mfma_f32_16x16x32_bf16 v[32:35], v[192:195], v[218:221], v[32:35]
	v_mfma_f32_16x16x32_bf16 v[36:39], v[184:187], v[218:221], v[36:39]
	v_mfma_f32_16x16x32_bf16 v[20:23], v[184:187], v[228:231], v[20:23]
	v_mfma_f32_16x16x32_bf16 v[16:19], v[192:195], v[228:231], v[16:19]
	v_mfma_f32_16x16x32_bf16 v[0:3], v[192:195], v[236:239], v[0:3]
	v_mfma_f32_16x16x32_bf16 v[4:7], v[184:187], v[236:239], v[4:7]
	s_setprio 0
	s_barrier
	s_add_i32 s82, s82, 2
	s_add_u32 s80, s80, 0x100
	s_addc_u32 s81, s81, 0
	s_add_u32 s60, s60, 0x100
	s_addc_u32 s61, s61, 0
	s_cmp_gt_u32 s82, 5
	s_cbranch_scc0 .LBB0_725
	s_and_b64 vcc, exec, s[16:17]
	s_cbranch_vccz .LBB0_728
	s_barrier

.LBB0_822:
	s_add_u32 s62, s60, 0xfffc0080
	s_addc_u32 s63, s61, -1
	s_add_i32 s86, 0, 0x10000
	s_cmp_eq_u32 s85, 12
	s_cselect_b32 s67, s21, s63
	s_cselect_b32 s66, s81, s62
	s_cselect_b32 s63, s19, s84
	s_cselect_b32 s62, s82, s83
	s_add_i32 s89, 0, 0x14000
	v_add_u32_e32 v124, s86, v210
	v_add_u32_e32 v186, s89, v210
	ds_read_b128 v[112:115], v124
	ds_read_b128 v[116:119], v124 offset:1024
	ds_read_b128 v[120:123], v124 offset:2048
	ds_read_b128 v[124:127], v124 offset:3072
	ds_read_b128 v[132:135], v186
	ds_read_b128 v[140:143], v186 offset:1024
	ds_read_b128 v[182:185], v186 offset:2048
	ds_read_b128 v[186:189], v186 offset:3072
	v_lshl_add_u64 v[198:199], s[60:61], 0, v[180:181]
	s_add_i32 m0, s68, 0xc000
	ds_read_b128 v[190:193], v212
	ds_read_b128 v[194:197], v212 offset:1024
	ds_read_b128 v[214:217], v212 offset:2048
	ds_read_b128 v[218:221], v212 offset:3072
	ds_read_b128 v[224:227], v212 offset:4096
	ds_read_b128 v[228:231], v212 offset:5120
	ds_read_b128 v[232:235], v212 offset:6144
	ds_read_b128 v[236:239], v212 offset:7168
	global_load_lds_dwordx4 v[198:199], off
	v_lshl_add_u64 v[198:199], s[60:61], 0, v[178:179]
	s_add_i32 m0, s68, 0xe000
	s_nop 0
	global_load_lds_dwordx4 v[198:199], off
	s_waitcnt vmcnt(8)
	s_waitcnt lgkmcnt(0)
	s_barrier
	s_setprio 1
	s_waitcnt lgkmcnt(0)
	v_mfma_f32_16x16x32_bf16 v[148:151], v[112:115], v[190:193], v[148:151]
	v_mfma_f32_16x16x32_bf16 v[144:147], v[120:123], v[190:193], v[144:147]
	v_mfma_f32_16x16x32_bf16 v[104:107], v[120:123], v[214:217], v[104:107]
	v_mfma_f32_16x16x32_bf16 v[108:111], v[112:115], v[214:217], v[108:111]
	v_mfma_f32_16x16x32_bf16 v[92:95], v[112:115], v[224:227], v[92:95]
	v_mfma_f32_16x16x32_bf16 v[88:91], v[120:123], v[224:227], v[88:91]
	v_mfma_f32_16x16x32_bf16 v[72:75], v[120:123], v[232:235], v[72:75]
	v_mfma_f32_16x16x32_bf16 v[76:79], v[112:115], v[232:235], v[76:79]
	v_mfma_f32_16x16x32_bf16 v[148:151], v[116:119], v[194:197], v[148:151]
	v_mfma_f32_16x16x32_bf16 v[144:147], v[124:127], v[194:197], v[144:147]
	v_mfma_f32_16x16x32_bf16 v[104:107], v[124:127], v[218:221], v[104:107]
	v_mfma_f32_16x16x32_bf16 v[108:111], v[116:119], v[218:221], v[108:111]
	v_mfma_f32_16x16x32_bf16 v[92:95], v[116:119], v[228:231], v[92:95]
	v_mfma_f32_16x16x32_bf16 v[88:91], v[124:127], v[228:231], v[88:91]
	v_mfma_f32_16x16x32_bf16 v[72:75], v[124:127], v[236:239], v[72:75]
	v_mfma_f32_16x16x32_bf16 v[76:79], v[116:119], v[236:239], v[76:79]
	s_setprio 0
	s_setprio 1
	v_mfma_f32_16x16x32_bf16 v[136:139], v[132:135], v[190:193], v[136:139]
	v_mfma_f32_16x16x32_bf16 v[128:131], v[182:185], v[190:193], v[128:131]
	v_mfma_f32_16x16x32_bf16 v[96:99], v[182:185], v[214:217], v[96:99]
	v_mfma_f32_16x16x32_bf16 v[100:103], v[132:135], v[214:217], v[100:103]
	v_mfma_f32_16x16x32_bf16 v[84:87], v[132:135], v[224:227], v[84:87]
	v_mfma_f32_16x16x32_bf16 v[80:83], v[182:185], v[224:227], v[80:83]
	v_mfma_f32_16x16x32_bf16 v[64:67], v[182:185], v[232:235], v[64:67]
	v_mfma_f32_16x16x32_bf16 v[68:71], v[132:135], v[232:235], v[68:71]
	v_mfma_f32_16x16x32_bf16 v[136:139], v[140:143], v[194:197], v[136:139]
	v_mfma_f32_16x16x32_bf16 v[128:131], v[186:189], v[194:197], v[128:131]
	v_mfma_f32_16x16x32_bf16 v[96:99], v[186:189], v[218:221], v[96:99]
	v_mfma_f32_16x16x32_bf16 v[100:103], v[140:143], v[218:221], v[100:103]
	v_mfma_f32_16x16x32_bf16 v[84:87], v[140:143], v[228:231], v[84:87]
	v_mfma_f32_16x16x32_bf16 v[80:83], v[186:189], v[228:231], v[80:83]
	v_mfma_f32_16x16x32_bf16 v[64:67], v[186:189], v[236:239], v[64:67]
	v_mfma_f32_16x16x32_bf16 v[68:71], v[140:143], v[236:239], v[68:71]
	s_setprio 0
	s_barrier
	s_add_i32 s86, s86, s59
	v_lshl_add_u64 v[198:199], s[62:63], 0, v[152:153]
	s_mov_b32 m0, s86
	ds_read_b128 v[190:193], v212 offset:16384
	ds_read_b128 v[194:197], v212 offset:17408
	ds_read_b128 v[214:217], v212 offset:18432
	ds_read_b128 v[218:221], v212 offset:19456
	ds_read_b128 v[224:227], v212 offset:20480
	ds_read_b128 v[228:231], v212 offset:21504
	ds_read_b128 v[232:235], v212 offset:22528
	ds_read_b128 v[236:239], v212 offset:23552
	global_load_lds_dwordx4 v[198:199], off
	s_add_i32 m0, s86, 0x2000
	s_add_u32 s86, s62, 0x40000
	v_lshl_add_u64 v[240:241], s[62:63], 0, v[172:173]
	s_addc_u32 s87, s63, 0
	s_add_i32 s89, s89, s59
	global_load_lds_dwordx4 v[240:241], off
	v_lshl_add_u64 v[242:243], s[86:87], 0, v[152:153]
	s_mov_b32 m0, s89
	v_lshl_add_u64 v[244:245], s[66:67], 0, v[174:175]
	global_load_lds_dwordx4 v[242:243], off
	v_lshl_add_u64 v[242:243], s[86:87], 0, v[172:173]
	s_add_i32 m0, s89, 0x2000
	s_nop 0
	global_load_lds_dwordx4 v[242:243], off
	v_lshl_add_u64 v[242:243], s[66:67], 0, v[176:177]
	s_mov_b32 m0, s68
	s_nop 0
	global_load_lds_dwordx4 v[242:243], off
	s_mov_b32 m0, s69
	s_nop 0
	global_load_lds_dwordx4 v[244:245], off
	s_waitcnt vmcnt(8)
	s_waitcnt lgkmcnt(0)
	s_barrier
	s_setprio 1
	s_waitcnt lgkmcnt(0)
	v_mfma_f32_16x16x32_bf16 v[60:63], v[112:115], v[190:193], v[60:63]
	v_mfma_f32_16x16x32_bf16 v[56:59], v[120:123], v[190:193], v[56:59]
	v_mfma_f32_16x16x32_bf16 v[40:43], v[120:123], v[214:217], v[40:43]
	v_mfma_f32_16x16x32_bf16 v[44:47], v[112:115], v[214:217], v[44:47]
	v_mfma_f32_16x16x32_bf16 v[28:31], v[112:115], v[224:227], v[28:31]
	v_mfma_f32_16x16x32_bf16 v[24:27], v[120:123], v[224:227], v[24:27]
	v_mfma_f32_16x16x32_bf16 v[8:11], v[120:123], v[232:235], v[8:11]
	v_mfma_f32_16x16x32_bf16 v[12:15], v[112:115], v[232:235], v[12:15]
	v_mfma_f32_16x16x32_bf16 v[60:63], v[116:119], v[194:197], v[60:63]
	v_mfma_f32_16x16x32_bf16 v[56:59], v[124:127], v[194:197], v[56:59]
	v_mfma_f32_16x16x32_bf16 v[40:43], v[124:127], v[218:221], v[40:43]
	v_mfma_f32_16x16x32_bf16 v[44:47], v[116:119], v[218:221], v[44:47]
	v_mfma_f32_16x16x32_bf16 v[28:31], v[116:119], v[228:231], v[28:31]
	v_mfma_f32_16x16x32_bf16 v[24:27], v[124:127], v[228:231], v[24:27]
	v_mfma_f32_16x16x32_bf16 v[8:11], v[124:127], v[236:239], v[8:11]
	v_mfma_f32_16x16x32_bf16 v[12:15], v[116:119], v[236:239], v[12:15]
	s_setprio 0
	s_setprio 1
	v_mfma_f32_16x16x32_bf16 v[52:55], v[132:135], v[190:193], v[52:55]
	v_mfma_f32_16x16x32_bf16 v[48:51], v[182:185], v[190:193], v[48:51]
	v_mfma_f32_16x16x32_bf16 v[32:35], v[182:185], v[214:217], v[32:35]
	v_mfma_f32_16x16x32_bf16 v[36:39], v[132:135], v[214:217], v[36:39]
	v_mfma_f32_16x16x32_bf16 v[20:23], v[132:135], v[224:227], v[20:23]
	v_mfma_f32_16x16x32_bf16 v[16:19], v[182:185], v[224:227], v[16:19]
	v_mfma_f32_16x16x32_bf16 v[0:3], v[182:185], v[232:235], v[0:3]
	v_mfma_f32_16x16x32_bf16 v[4:7], v[132:135], v[232:235], v[4:7]
	v_mfma_f32_16x16x32_bf16 v[52:55], v[140:143], v[194:197], v[52:55]
	v_mfma_f32_16x16x32_bf16 v[48:51], v[186:189], v[194:197], v[48:51]
	v_mfma_f32_16x16x32_bf16 v[32:35], v[186:189], v[218:221], v[32:35]
	v_mfma_f32_16x16x32_bf16 v[36:39], v[140:143], v[218:221], v[36:39]
	v_mfma_f32_16x16x32_bf16 v[20:23], v[140:143], v[228:231], v[20:23]
	v_mfma_f32_16x16x32_bf16 v[16:19], v[186:189], v[228:231], v[16:19]
	v_mfma_f32_16x16x32_bf16 v[0:3], v[186:189], v[236:239], v[0:3]
	v_mfma_f32_16x16x32_bf16 v[4:7], v[140:143], v[236:239], v[4:7]
	s_setprio 0
	s_barrier
	s_add_i32 s86, 0, 0x18000
	s_add_i32 s87, 0, 0x1c000
	v_add_u32_e32 v124, s86, v210
	v_add_u32_e32 v186, s87, v210
	ds_read_b128 v[112:115], v124
	ds_read_b128 v[116:119], v124 offset:1024
	ds_read_b128 v[120:123], v124 offset:2048
	ds_read_b128 v[124:127], v124 offset:3072
	ds_read_b128 v[132:135], v186
	ds_read_b128 v[140:143], v186 offset:1024
	ds_read_b128 v[182:185], v186 offset:2048
	ds_read_b128 v[186:189], v186 offset:3072
	s_add_u32 s66, s66, 0x40000
	s_addc_u32 s67, s67, 0
	s_mov_b32 m0, s74
	v_lshl_add_u64 v[246:247], s[66:67], 0, v[176:177]
	ds_read_b128 v[190:193], v212 offset:32768
	ds_read_b128 v[194:197], v212 offset:33792
	ds_read_b128 v[214:217], v212 offset:34816
	ds_read_b128 v[218:221], v212 offset:35840
	ds_read_b128 v[224:227], v212 offset:36864
	ds_read_b128 v[228:231], v212 offset:37888
	ds_read_b128 v[232:235], v212 offset:38912
	ds_read_b128 v[236:239], v212 offset:39936
	global_load_lds_dwordx4 v[246:247], off
	v_lshl_add_u64 v[246:247], s[66:67], 0, v[174:175]
	s_mov_b32 m0, s75
	s_nop 0
	global_load_lds_dwordx4 v[246:247], off
	s_waitcnt vmcnt(8)
	s_waitcnt lgkmcnt(0)
	s_barrier
	s_setprio 1
	s_waitcnt lgkmcnt(0)
	v_mfma_f32_16x16x32_bf16 v[148:151], v[112:115], v[190:193], v[148:151]
	v_mfma_f32_16x16x32_bf16 v[144:147], v[120:123], v[190:193], v[144:147]
	v_mfma_f32_16x16x32_bf16 v[104:107], v[120:123], v[214:217], v[104:107]
	v_mfma_f32_16x16x32_bf16 v[108:111], v[112:115], v[214:217], v[108:111]
	v_mfma_f32_16x16x32_bf16 v[92:95], v[112:115], v[224:227], v[92:95]
	v_mfma_f32_16x16x32_bf16 v[88:91], v[120:123], v[224:227], v[88:91]
	v_mfma_f32_16x16x32_bf16 v[72:75], v[120:123], v[232:235], v[72:75]
	v_mfma_f32_16x16x32_bf16 v[76:79], v[112:115], v[232:235], v[76:79]
	v_mfma_f32_16x16x32_bf16 v[148:151], v[116:119], v[194:197], v[148:151]
	v_mfma_f32_16x16x32_bf16 v[144:147], v[124:127], v[194:197], v[144:147]
	v_mfma_f32_16x16x32_bf16 v[104:107], v[124:127], v[218:221], v[104:107]
	v_mfma_f32_16x16x32_bf16 v[108:111], v[116:119], v[218:221], v[108:111]
	v_mfma_f32_16x16x32_bf16 v[92:95], v[116:119], v[228:231], v[92:95]
	v_mfma_f32_16x16x32_bf16 v[88:91], v[124:127], v[228:231], v[88:91]
	v_mfma_f32_16x16x32_bf16 v[72:75], v[124:127], v[236:239], v[72:75]
	v_mfma_f32_16x16x32_bf16 v[76:79], v[116:119], v[236:239], v[76:79]
	s_setprio 0
	s_setprio 1
	v_mfma_f32_16x16x32_bf16 v[136:139], v[132:135], v[190:193], v[136:139]
	v_mfma_f32_16x16x32_bf16 v[128:131], v[182:185], v[190:193], v[128:131]
	v_mfma_f32_16x16x32_bf16 v[96:99], v[182:185], v[214:217], v[96:99]
	v_mfma_f32_16x16x32_bf16 v[100:103], v[132:135], v[214:217], v[100:103]
	v_mfma_f32_16x16x32_bf16 v[84:87], v[132:135], v[224:227], v[84:87]
	v_mfma_f32_16x16x32_bf16 v[80:83], v[182:185], v[224:227], v[80:83]
	v_mfma_f32_16x16x32_bf16 v[64:67], v[182:185], v[232:235], v[64:67]
	v_mfma_f32_16x16x32_bf16 v[68:71], v[132:135], v[232:235], v[68:71]
	v_mfma_f32_16x16x32_bf16 v[136:139], v[140:143], v[194:197], v[136:139]
	v_mfma_f32_16x16x32_bf16 v[128:131], v[186:189], v[194:197], v[128:131]
	v_mfma_f32_16x16x32_bf16 v[96:99], v[186:189], v[218:221], v[96:99]
	v_mfma_f32_16x16x32_bf16 v[100:103], v[140:143], v[218:221], v[100:103]
	v_mfma_f32_16x16x32_bf16 v[84:87], v[140:143], v[228:231], v[84:87]
	v_mfma_f32_16x16x32_bf16 v[80:83], v[186:189], v[228:231], v[80:83]
	v_mfma_f32_16x16x32_bf16 v[64:67], v[186:189], v[236:239], v[64:67]
	v_mfma_f32_16x16x32_bf16 v[68:71], v[140:143], v[236:239], v[68:71]
	s_setprio 0
	s_barrier
	s_add_i32 s66, s86, s59
	v_lshl_add_u64 v[198:199], v[198:199], 0, s[22:23]
	s_mov_b32 m0, s66
	ds_read_b128 v[190:193], v212 offset:49152
	ds_read_b128 v[194:197], v212 offset:50176
	ds_read_b128 v[214:217], v212 offset:51200
	ds_read_b128 v[218:221], v212 offset:52224
	ds_read_b128 v[224:227], v212 offset:53248
	ds_read_b128 v[228:231], v212 offset:54272
	ds_read_b128 v[232:235], v212 offset:55296
	ds_read_b128 v[236:239], v212 offset:56320
	global_load_lds_dwordx4 v[198:199], off
	s_add_i32 m0, s66, 0x2000
	s_add_u32 s62, s62, 0x40080
	v_lshl_add_u64 v[198:199], v[240:241], 0, s[22:23]
	s_addc_u32 s63, s63, 0
	s_add_i32 s66, s87, s59
	global_load_lds_dwordx4 v[198:199], off
	v_lshl_add_u64 v[198:199], s[62:63], 0, v[152:153]
	s_mov_b32 m0, s66
	s_nop 0
	global_load_lds_dwordx4 v[198:199], off
	v_lshl_add_u64 v[198:199], s[62:63], 0, v[172:173]
	s_add_i32 m0, s66, 0x2000
	s_nop 0
	global_load_lds_dwordx4 v[198:199], off
	v_lshl_add_u64 v[198:199], v[242:243], 0, s[22:23]
	s_mov_b32 m0, s77
	s_nop 0
	global_load_lds_dwordx4 v[198:199], off
	v_lshl_add_u64 v[198:199], v[244:245], 0, s[22:23]
	s_mov_b32 m0, s78
	s_nop 0
	global_load_lds_dwordx4 v[198:199], off
	s_waitcnt vmcnt(8)
	s_waitcnt lgkmcnt(0)
	s_barrier
	s_setprio 1
	s_waitcnt lgkmcnt(0)
	v_mfma_f32_16x16x32_bf16 v[60:63], v[112:115], v[190:193], v[60:63]
	v_mfma_f32_16x16x32_bf16 v[56:59], v[120:123], v[190:193], v[56:59]
	v_mfma_f32_16x16x32_bf16 v[40:43], v[120:123], v[214:217], v[40:43]
	v_mfma_f32_16x16x32_bf16 v[44:47], v[112:115], v[214:217], v[44:47]
	v_mfma_f32_16x16x32_bf16 v[28:31], v[112:115], v[224:227], v[28:31]
	v_mfma_f32_16x16x32_bf16 v[24:27], v[120:123], v[224:227], v[24:27]
	v_mfma_f32_16x16x32_bf16 v[8:11], v[120:123], v[232:235], v[8:11]
	v_mfma_f32_16x16x32_bf16 v[12:15], v[112:115], v[232:235], v[12:15]
	v_mfma_f32_16x16x32_bf16 v[60:63], v[116:119], v[194:197], v[60:63]
	v_mfma_f32_16x16x32_bf16 v[56:59], v[124:127], v[194:197], v[56:59]
	v_mfma_f32_16x16x32_bf16 v[40:43], v[124:127], v[218:221], v[40:43]
	v_mfma_f32_16x16x32_bf16 v[44:47], v[116:119], v[218:221], v[44:47]
	v_mfma_f32_16x16x32_bf16 v[28:31], v[116:119], v[228:231], v[28:31]
	v_mfma_f32_16x16x32_bf16 v[24:27], v[124:127], v[228:231], v[24:27]
	v_mfma_f32_16x16x32_bf16 v[8:11], v[124:127], v[236:239], v[8:11]
	v_mfma_f32_16x16x32_bf16 v[12:15], v[116:119], v[236:239], v[12:15]
	s_setprio 0
	s_setprio 1
	v_mfma_f32_16x16x32_bf16 v[52:55], v[132:135], v[190:193], v[52:55]
	v_mfma_f32_16x16x32_bf16 v[48:51], v[182:185], v[190:193], v[48:51]
	v_mfma_f32_16x16x32_bf16 v[32:35], v[182:185], v[214:217], v[32:35]
	v_mfma_f32_16x16x32_bf16 v[36:39], v[132:135], v[214:217], v[36:39]
	v_mfma_f32_16x16x32_bf16 v[20:23], v[132:135], v[224:227], v[20:23]
	v_mfma_f32_16x16x32_bf16 v[16:19], v[182:185], v[224:227], v[16:19]
	v_mfma_f32_16x16x32_bf16 v[0:3], v[182:185], v[232:235], v[0:3]
	v_mfma_f32_16x16x32_bf16 v[4:7], v[132:135], v[232:235], v[4:7]
	v_mfma_f32_16x16x32_bf16 v[52:55], v[140:143], v[194:197], v[52:55]
	v_mfma_f32_16x16x32_bf16 v[48:51], v[186:189], v[194:197], v[48:51]
	v_mfma_f32_16x16x32_bf16 v[32:35], v[186:189], v[218:221], v[32:35]
	v_mfma_f32_16x16x32_bf16 v[36:39], v[140:143], v[218:221], v[36:39]
	v_mfma_f32_16x16x32_bf16 v[20:23], v[140:143], v[228:231], v[20:23]
	v_mfma_f32_16x16x32_bf16 v[16:19], v[186:189], v[228:231], v[16:19]
	v_mfma_f32_16x16x32_bf16 v[0:3], v[186:189], v[236:239], v[0:3]
	v_mfma_f32_16x16x32_bf16 v[4:7], v[140:143], v[236:239], v[4:7]
	s_setprio 0
	s_barrier
	s_add_i32 s85, s85, 2
	s_add_u32 s83, s83, 0x100
	s_addc_u32 s84, s84, 0
	s_add_u32 s60, s60, 0x100
	s_addc_u32 s61, s61, 0
	s_cmp_gt_u32 s85, 13
	s_cbranch_scc0 .LBB0_822
	s_and_b64 vcc, exec, s[16:17]
	s_cbranch_vccz .LBB0_825
	s_barrier
